# HGRN2 scan: state carried as S - v(next) so each state element costs one packed FMA per step plus one for the output; output adds v(next) * sum(q)
# speedup vs baseline: 1.0215x; 1.0155x over previous
; __device__ __forceinline__ float bf2f(unsigned short b) { return __uint_as_float((unsigned)b << 16); }
; __device__ __forceinline__ float sigm(float x) { return __builtin_amdgcn_rcpf(1.0f + __expf(-x)); }
; __device__ __forceinline__ void hgrn_scan(const bf16_t* __restrict__ PH, int t0, int nsteps, int h, int half, int kh, int lane, float lb, f2 (&S)[32], float& cp, bf16_t* __restrict__ OHp, float* __restrict__ ckp, LAS float* L) {
;     const bf16_t* row = PH + (size_t)t0 * 2048 + h * 128 + kh * 64 + lane; const int voff = 1024 + (half - kh) * 64;
;     unsigned short q1[3], q2[3], q3[3];
;     { const bf16_t* r = row; q1[0] = r[0]; q1[1] = r[512]; q1[2] = r[voff];
;       r = row + 2048; q2[0] = r[0]; q2[1] = r[512]; q2[2] = r[voff];
;       r = row + 4096; q3[0] = r[0]; q3[1] = r[512]; q3[2] = r[voff]; }
;     const LAS f32x4* pf = (const LAS f32x4*)L;
; #pragma unroll 1
;     for (int s = 0; s < nsteps; ++s) {
;         const float ql = bf2f(q1[0]), fz = bf2f(q1[1]), v = bf2f(q1[2]);
; #pragma unroll
;         for (int j = 0; j < 3; ++j) { q1[j] = q2[j]; q2[j] = q3[j]; }
;         { const bf16_t* r = row + (size_t)(s + 3 < nsteps ? s + 3 : nsteps - 1) * 2048; q3[0] = r[0]; q3[1] = r[512]; q3[2] = r[voff]; }
;         const float fl = lb + (1.0f - lb) * sigm(fz);
;         cp *= fl;
;         if (ckp && (s & 31) == 31 && s < 127) ckp[(s >> 5) * 128 + lane] = cp;
;         L[lane] = fl; L[64 + lane] = ql * sigm(ql);
;         f32x4 F[2][4], Q[2][4];
; #pragma unroll
;         for (int i = 0; i < 4; ++i) { F[0][i] = pf[i]; Q[0][i] = pf[16 + i]; }
;         const f2 v2 = {v, v}; f2 o2 = {0.f, 0.f}, o3 = {0.f, 0.f};
.Lhs_go:
	global_load_ushort v224, v136, s[24:25]
	global_load_ushort v225, v136, s[24:25] offset:1024
	global_load_ushort v226, v137, s[24:25]
	global_load_ushort v227, v137, s[24:25] offset:128
	v_add_u32_e32 v136, 0x1000, v136
	v_add_u32_e32 v137, 0x1000, v137
	global_load_ushort v228, v136, s[24:25]
	global_load_ushort v229, v136, s[24:25] offset:1024
	global_load_ushort v230, v137, s[24:25]
	global_load_ushort v231, v137, s[24:25] offset:128
	v_add_u32_e32 v136, 0x1000, v136
	v_add_u32_e32 v137, 0x1000, v137
	global_load_ushort v232, v136, s[24:25]
	global_load_ushort v233, v136, s[24:25] offset:1024
	global_load_ushort v234, v137, s[24:25]
	global_load_ushort v235, v137, s[24:25] offset:128
	v_add_u32_e32 v136, 0x1000, v136
	v_add_u32_e32 v137, 0x1000, v137
	global_load_ushort v236, v136, s[24:25]
	global_load_ushort v237, v136, s[24:25] offset:1024
	global_load_ushort v238, v137, s[24:25]
	global_load_ushort v239, v137, s[24:25] offset:128
	v_add_u32_e32 v136, 0x1000, v136
	v_add_u32_e32 v137, 0x1000, v137
	s_waitcnt vmcnt(8)
	v_lshlrev_b32_e32 v140, 16, v225
	v_lshlrev_b32_e32 v141, 16, v224
	v_mul_f32_e32 v142, 0xbfb8aa3b, v140
	v_mul_f32_e32 v143, 0xbfb8aa3b, v141
	v_exp_f32_e32 v142, v142
	v_exp_f32_e32 v143, v143
	v_add_f32_e32 v142, 1.0, v142
	v_add_f32_e32 v143, 1.0, v143
	v_rcp_f32_e32 v142, v142
	v_rcp_f32_e32 v143, v143
	v_fma_f32 v142, v131, v142, v130
	v_mul_f32_e32 v143, v143, v141
	v_mul_f32_e32 v132, v132, v142
	ds_write2st64_b32 v134, v142, v143 offset0:0 offset1:1
	v_mov_b32_e32 v182, v143
	v_lshlrev_b32_e32 v140, 16, v226
	v_lshlrev_b32_e32 v141, 16, v227
	v_lshlrev_b32_e32 v254, 16, v230
	v_lshlrev_b32_e32 v255, 16, v231
	v_pk_add_f32 v[0:1], v[0:1], v[140:141] op_sel_hi:[1,0] neg_lo:[0,1] neg_hi:[0,1]
	v_pk_add_f32 v[2:3], v[2:3], v[140:141] op_sel_hi:[1,0] neg_lo:[0,1] neg_hi:[0,1]
	v_pk_add_f32 v[4:5], v[4:5], v[140:141] op_sel_hi:[1,0] neg_lo:[0,1] neg_hi:[0,1]
	v_pk_add_f32 v[6:7], v[6:7], v[140:141] op_sel_hi:[1,0] neg_lo:[0,1] neg_hi:[0,1]
	v_pk_add_f32 v[8:9], v[8:9], v[140:141] op_sel_hi:[1,0] neg_lo:[0,1] neg_hi:[0,1]
	v_pk_add_f32 v[10:11], v[10:11], v[140:141] op_sel_hi:[1,0] neg_lo:[0,1] neg_hi:[0,1]
	v_pk_add_f32 v[12:13], v[12:13], v[140:141] op_sel_hi:[1,0] neg_lo:[0,1] neg_hi:[0,1]
	v_pk_add_f32 v[14:15], v[14:15], v[140:141] op_sel_hi:[1,0] neg_lo:[0,1] neg_hi:[0,1]
	v_pk_add_f32 v[16:17], v[16:17], v[140:141] op_sel_hi:[1,0] neg_lo:[0,1] neg_hi:[0,1]
	v_pk_add_f32 v[18:19], v[18:19], v[140:141] op_sel_hi:[1,0] neg_lo:[0,1] neg_hi:[0,1]
	v_pk_add_f32 v[20:21], v[20:21], v[140:141] op_sel_hi:[1,0] neg_lo:[0,1] neg_hi:[0,1]
	v_pk_add_f32 v[22:23], v[22:23], v[140:141] op_sel_hi:[1,0] neg_lo:[0,1] neg_hi:[0,1]
	v_pk_add_f32 v[24:25], v[24:25], v[140:141] op_sel_hi:[1,0] neg_lo:[0,1] neg_hi:[0,1]
	v_pk_add_f32 v[26:27], v[26:27], v[140:141] op_sel_hi:[1,0] neg_lo:[0,1] neg_hi:[0,1]
	v_pk_add_f32 v[28:29], v[28:29], v[140:141] op_sel_hi:[1,0] neg_lo:[0,1] neg_hi:[0,1]
	v_pk_add_f32 v[30:31], v[30:31], v[140:141] op_sel_hi:[1,0] neg_lo:[0,1] neg_hi:[0,1]
	v_pk_add_f32 v[32:33], v[32:33], v[140:141] op_sel_hi:[1,0] neg_lo:[0,1] neg_hi:[0,1]
	v_pk_add_f32 v[34:35], v[34:35], v[140:141] op_sel_hi:[1,0] neg_lo:[0,1] neg_hi:[0,1]
	v_pk_add_f32 v[36:37], v[36:37], v[140:141] op_sel_hi:[1,0] neg_lo:[0,1] neg_hi:[0,1]
	v_pk_add_f32 v[38:39], v[38:39], v[140:141] op_sel_hi:[1,0] neg_lo:[0,1] neg_hi:[0,1]
	v_pk_add_f32 v[40:41], v[40:41], v[140:141] op_sel_hi:[1,0] neg_lo:[0,1] neg_hi:[0,1]
	v_pk_add_f32 v[42:43], v[42:43], v[140:141] op_sel_hi:[1,0] neg_lo:[0,1] neg_hi:[0,1]
	v_pk_add_f32 v[44:45], v[44:45], v[140:141] op_sel_hi:[1,0] neg_lo:[0,1] neg_hi:[0,1]
	v_pk_add_f32 v[46:47], v[46:47], v[140:141] op_sel_hi:[1,0] neg_lo:[0,1] neg_hi:[0,1]
	v_pk_add_f32 v[48:49], v[48:49], v[140:141] op_sel_hi:[1,0] neg_lo:[0,1] neg_hi:[0,1]
	v_pk_add_f32 v[50:51], v[50:51], v[140:141] op_sel_hi:[1,0] neg_lo:[0,1] neg_hi:[0,1]
	v_pk_add_f32 v[52:53], v[52:53], v[140:141] op_sel_hi:[1,0] neg_lo:[0,1] neg_hi:[0,1]
	v_pk_add_f32 v[54:55], v[54:55], v[140:141] op_sel_hi:[1,0] neg_lo:[0,1] neg_hi:[0,1]
	v_pk_add_f32 v[56:57], v[56:57], v[140:141] op_sel_hi:[1,0] neg_lo:[0,1] neg_hi:[0,1]
	v_pk_add_f32 v[58:59], v[58:59], v[140:141] op_sel_hi:[1,0] neg_lo:[0,1] neg_hi:[0,1]
	v_pk_add_f32 v[60:61], v[60:61], v[140:141] op_sel_hi:[1,0] neg_lo:[0,1] neg_hi:[0,1]
	v_pk_add_f32 v[62:63], v[62:63], v[140:141] op_sel_hi:[1,0] neg_lo:[0,1] neg_hi:[0,1]
	v_pk_add_f32 v[64:65], v[64:65], v[140:141] op_sel:[0,1] op_sel_hi:[1,1] neg_lo:[0,1] neg_hi:[0,1]
	v_pk_add_f32 v[66:67], v[66:67], v[140:141] op_sel:[0,1] op_sel_hi:[1,1] neg_lo:[0,1] neg_hi:[0,1]
	v_pk_add_f32 v[68:69], v[68:69], v[140:141] op_sel:[0,1] op_sel_hi:[1,1] neg_lo:[0,1] neg_hi:[0,1]
	v_pk_add_f32 v[70:71], v[70:71], v[140:141] op_sel:[0,1] op_sel_hi:[1,1] neg_lo:[0,1] neg_hi:[0,1]
	v_pk_add_f32 v[72:73], v[72:73], v[140:141] op_sel:[0,1] op_sel_hi:[1,1] neg_lo:[0,1] neg_hi:[0,1]
	v_pk_add_f32 v[74:75], v[74:75], v[140:141] op_sel:[0,1] op_sel_hi:[1,1] neg_lo:[0,1] neg_hi:[0,1]
	v_pk_add_f32 v[76:77], v[76:77], v[140:141] op_sel:[0,1] op_sel_hi:[1,1] neg_lo:[0,1] neg_hi:[0,1]
	v_pk_add_f32 v[78:79], v[78:79], v[140:141] op_sel:[0,1] op_sel_hi:[1,1] neg_lo:[0,1] neg_hi:[0,1]
	v_pk_add_f32 v[80:81], v[80:81], v[140:141] op_sel:[0,1] op_sel_hi:[1,1] neg_lo:[0,1] neg_hi:[0,1]
	v_pk_add_f32 v[82:83], v[82:83], v[140:141] op_sel:[0,1] op_sel_hi:[1,1] neg_lo:[0,1] neg_hi:[0,1]
	v_pk_add_f32 v[84:85], v[84:85], v[140:141] op_sel:[0,1] op_sel_hi:[1,1] neg_lo:[0,1] neg_hi:[0,1]
	v_pk_add_f32 v[86:87], v[86:87], v[140:141] op_sel:[0,1] op_sel_hi:[1,1] neg_lo:[0,1] neg_hi:[0,1]
; __device__ __forceinline__ float bf2f(unsigned short b) { return __uint_as_float((unsigned)b << 16); }
; __device__ __forceinline__ float sigm(float x) { return __builtin_amdgcn_rcpf(1.0f + __expf(-x)); }
; __device__ __forceinline__ f2 pfma(f2 a, f2 b, f2 c) { return __builtin_elementwise_fma(a, b, c); }
; __device__ __forceinline__ void hgrn_scan(const bf16_t* __restrict__ PH, int t0, int nsteps, int h, int half, int kh, int lane, float lb, f2 (&S)[32], float& cp, bf16_t* __restrict__ OHp, float* __restrict__ ckp, LAS float* L) {
;     ...
;     for (int s = 0; s < nsteps; ++s) {
;         const float ql = bf2f(q1[0]), fz = bf2f(q1[1]), v = bf2f(q1[2]);
; #pragma unroll
;         for (int j = 0; j < 3; ++j) { q1[j] = q2[j]; q2[j] = q3[j]; }
;         { const bf16_t* r = row + (size_t)(s + 3 < nsteps ? s + 3 : nsteps - 1) * 2048; q3[0] = r[0]; q3[1] = r[512]; q3[2] = r[voff]; }
;         const float fl = lb + (1.0f - lb) * sigm(fz);
;         cp *= fl;
;         if (ckp && (s & 31) == 31 && s < 127) ckp[(s >> 5) * 128 + lane] = cp;
;         L[lane] = fl; L[64 + lane] = ql * sigm(ql);
;         f32x4 F[2][4], Q[2][4];
; #pragma unroll
;         for (int i = 0; i < 4; ++i) { F[0][i] = pf[i]; Q[0][i] = pf[16 + i]; }
;         const f2 v2 = {v, v}; f2 o2 = {0.f, 0.f}, o3 = {0.f, 0.f};
; #pragma unroll
;         for (int g = 0; g < 4; ++g) {
;             if (g < 3) {
; #pragma unroll
;                 for (int i = 0; i < 4; ++i) { F[(g + 1) & 1][i] = pf[(g + 1) * 4 + i]; Q[(g + 1) & 1][i] = pf[16 + (g + 1) * 4 + i]; } }
;             __builtin_amdgcn_sched_barrier(0);
; #pragma unroll
;             for (int i = 0; i < 4; ++i) {
;                 const f32x4 f4 = F[g & 1][i], q4 = Q[g & 1][i]; const int idx = (g * 4 + i) * 2;
;                 const f2 f01 = {f4[0], f4[1]}, f23 = {f4[2], f4[3]}, q01 = {q4[0], q4[1]}, q23 = {q4[2], q4[3]};
;                 S[idx] = pfma(f01, S[idx] - v2, v2); o2 = pfma(S[idx], q01, o2);
;                 S[idx + 1] = pfma(f23, S[idx + 1] - v2, v2); o3 = pfma(S[idx + 1], q23, o3);
;             }
;         }
	v_pk_add_f32 v[88:89], v[88:89], v[140:141] op_sel:[0,1] op_sel_hi:[1,1] neg_lo:[0,1] neg_hi:[0,1]
	v_pk_add_f32 v[90:91], v[90:91], v[140:141] op_sel:[0,1] op_sel_hi:[1,1] neg_lo:[0,1] neg_hi:[0,1]
	v_pk_add_f32 v[92:93], v[92:93], v[140:141] op_sel:[0,1] op_sel_hi:[1,1] neg_lo:[0,1] neg_hi:[0,1]
	v_pk_add_f32 v[94:95], v[94:95], v[140:141] op_sel:[0,1] op_sel_hi:[1,1] neg_lo:[0,1] neg_hi:[0,1]
	v_pk_add_f32 v[96:97], v[96:97], v[140:141] op_sel:[0,1] op_sel_hi:[1,1] neg_lo:[0,1] neg_hi:[0,1]
	v_pk_add_f32 v[98:99], v[98:99], v[140:141] op_sel:[0,1] op_sel_hi:[1,1] neg_lo:[0,1] neg_hi:[0,1]
	v_pk_add_f32 v[100:101], v[100:101], v[140:141] op_sel:[0,1] op_sel_hi:[1,1] neg_lo:[0,1] neg_hi:[0,1]
	v_pk_add_f32 v[102:103], v[102:103], v[140:141] op_sel:[0,1] op_sel_hi:[1,1] neg_lo:[0,1] neg_hi:[0,1]
	v_pk_add_f32 v[104:105], v[104:105], v[140:141] op_sel:[0,1] op_sel_hi:[1,1] neg_lo:[0,1] neg_hi:[0,1]
	v_pk_add_f32 v[106:107], v[106:107], v[140:141] op_sel:[0,1] op_sel_hi:[1,1] neg_lo:[0,1] neg_hi:[0,1]
	v_pk_add_f32 v[108:109], v[108:109], v[140:141] op_sel:[0,1] op_sel_hi:[1,1] neg_lo:[0,1] neg_hi:[0,1]
	v_pk_add_f32 v[110:111], v[110:111], v[140:141] op_sel:[0,1] op_sel_hi:[1,1] neg_lo:[0,1] neg_hi:[0,1]
	v_pk_add_f32 v[112:113], v[112:113], v[140:141] op_sel:[0,1] op_sel_hi:[1,1] neg_lo:[0,1] neg_hi:[0,1]
	v_pk_add_f32 v[114:115], v[114:115], v[140:141] op_sel:[0,1] op_sel_hi:[1,1] neg_lo:[0,1] neg_hi:[0,1]
	v_pk_add_f32 v[116:117], v[116:117], v[140:141] op_sel:[0,1] op_sel_hi:[1,1] neg_lo:[0,1] neg_hi:[0,1]
	v_pk_add_f32 v[118:119], v[118:119], v[140:141] op_sel:[0,1] op_sel_hi:[1,1] neg_lo:[0,1] neg_hi:[0,1]
	v_pk_add_f32 v[120:121], v[120:121], v[140:141] op_sel:[0,1] op_sel_hi:[1,1] neg_lo:[0,1] neg_hi:[0,1]
	v_pk_add_f32 v[122:123], v[122:123], v[140:141] op_sel:[0,1] op_sel_hi:[1,1] neg_lo:[0,1] neg_hi:[0,1]
	v_pk_add_f32 v[124:125], v[124:125], v[140:141] op_sel:[0,1] op_sel_hi:[1,1] neg_lo:[0,1] neg_hi:[0,1]
	v_pk_add_f32 v[126:127], v[126:127], v[140:141] op_sel:[0,1] op_sel_hi:[1,1] neg_lo:[0,1] neg_hi:[0,1]
	v_pk_add_f32 v[250:251], v[140:141], v[254:255] neg_lo:[0,1] neg_hi:[0,1]
	v_add_f32_dpp v182, v182, v182 quad_perm:[1,0,3,2] row_mask:0xf bank_mask:0xf bound_ctrl:1
	s_nop 1
	v_add_f32_dpp v182, v182, v182 quad_perm:[2,3,0,1] row_mask:0xf bank_mask:0xf bound_ctrl:1
	s_nop 1
	v_add_f32_dpp v182, v182, v182 row_half_mirror row_mask:0xf bank_mask:0xf bound_ctrl:1
	s_nop 1
	v_add_f32_dpp v182, v182, v182 row_mirror row_mask:0xf bank_mask:0xf bound_ctrl:1
	s_nop 1
	v_readlane_b32 s0, v182, 0
	v_readlane_b32 s1, v182, 16
	v_readlane_b32 s6, v182, 32
	v_readlane_b32 s7, v182, 48
	s_nop 1
	v_mov_b32_e32 v183, s0
	v_add_f32_e32 v183, s1, v183
	v_add_f32_e32 v183, s6, v183
	v_add_f32_e32 v183, s7, v183
	s_nop 1
	v_readfirstlane_b32 s2, v183
	s_add_i32 s5, s36, -1
	s_mov_b32 s4, -1
	ds_read_b128 v[148:151], v135 offset:0
	ds_read_b128 v[152:155], v135 offset:16
	ds_read_b128 v[156:159], v135 offset:32
	ds_read_b128 v[160:163], v135 offset:48
	ds_read_b128 v[164:167], v135 offset:256
	ds_read_b128 v[168:171], v135 offset:272
	ds_read_b128 v[172:175], v135 offset:288
	ds_read_b128 v[176:179], v135 offset:304
	s_mov_b32 s37, 0
.Lhs_m_loop:
	global_load_ushort v224, v136, s[24:25]
	global_load_ushort v225, v136, s[24:25] offset:1024
	global_load_ushort v226, v137, s[24:25]
	global_load_ushort v227, v137, s[24:25] offset:128
	v_add_u32_e32 v136, 0x1000, v136
	v_add_u32_e32 v137, 0x1000, v137
	s_mov_b32 s4, -1
	ds_read_b128 v[192:195], v135 offset:64
	ds_read_b128 v[196:199], v135 offset:80
	ds_read_b128 v[200:203], v135 offset:96
	ds_read_b128 v[204:207], v135 offset:112
	ds_read_b128 v[208:211], v135 offset:320
	ds_read_b128 v[212:215], v135 offset:336
	ds_read_b128 v[216:219], v135 offset:352
	ds_read_b128 v[220:223], v135 offset:368
	s_waitcnt lgkmcnt(8)
	v_pk_fma_f32 v[0:1], v[148:149], v[0:1], v[250:251] op_sel_hi:[1,1,0]
	v_pk_fma_f32 v[2:3], v[150:151], v[2:3], v[250:251] op_sel_hi:[1,1,0]
	v_pk_fma_f32 v[4:5], v[152:153], v[4:5], v[250:251] op_sel_hi:[1,1,0]
	v_pk_fma_f32 v[6:7], v[154:155], v[6:7], v[250:251] op_sel_hi:[1,1,0]
	v_pk_fma_f32 v[240:241], v[0:1], v[164:165], 0 op_sel_hi:[1,1,0]
	v_pk_fma_f32 v[244:245], v[2:3], v[166:167], 0 op_sel_hi:[1,1,0]
	v_pk_fma_f32 v[240:241], v[4:5], v[168:169], v[240:241]
	v_pk_fma_f32 v[244:245], v[6:7], v[170:171], v[244:245]
	v_pk_fma_f32 v[8:9], v[156:157], v[8:9], v[250:251] op_sel_hi:[1,1,0]
	v_pk_fma_f32 v[10:11], v[158:159], v[10:11], v[250:251] op_sel_hi:[1,1,0]
	v_pk_fma_f32 v[12:13], v[160:161], v[12:13], v[250:251] op_sel_hi:[1,1,0]
	v_pk_fma_f32 v[14:15], v[162:163], v[14:15], v[250:251] op_sel_hi:[1,1,0]
	v_pk_fma_f32 v[240:241], v[8:9], v[172:173], v[240:241]
	v_pk_fma_f32 v[244:245], v[10:11], v[174:175], v[244:245]
	v_pk_fma_f32 v[240:241], v[12:13], v[176:177], v[240:241]
	v_pk_fma_f32 v[244:245], v[14:15], v[178:179], v[244:245]
	v_pk_fma_f32 v[64:65], v[148:149], v[64:65], v[250:251] op_sel:[0,0,1] op_sel_hi:[1,1,1]
	v_pk_fma_f32 v[66:67], v[150:151], v[66:67], v[250:251] op_sel:[0,0,1] op_sel_hi:[1,1,1]
	v_pk_fma_f32 v[68:69], v[152:153], v[68:69], v[250:251] op_sel:[0,0,1] op_sel_hi:[1,1,1]
	v_pk_fma_f32 v[70:71], v[154:155], v[70:71], v[250:251] op_sel:[0,0,1] op_sel_hi:[1,1,1]
	v_pk_fma_f32 v[246:247], v[64:65], v[164:165], 0 op_sel_hi:[1,1,0]
	v_pk_fma_f32 v[248:249], v[66:67], v[166:167], 0 op_sel_hi:[1,1,0]
	v_pk_fma_f32 v[246:247], v[68:69], v[168:169], v[246:247]
	v_pk_fma_f32 v[248:249], v[70:71], v[170:171], v[248:249]
	v_pk_fma_f32 v[72:73], v[156:157], v[72:73], v[250:251] op_sel:[0,0,1] op_sel_hi:[1,1,1]
	v_pk_fma_f32 v[74:75], v[158:159], v[74:75], v[250:251] op_sel:[0,0,1] op_sel_hi:[1,1,1]
	v_pk_fma_f32 v[76:77], v[160:161], v[76:77], v[250:251] op_sel:[0,0,1] op_sel_hi:[1,1,1]
	v_pk_fma_f32 v[78:79], v[162:163], v[78:79], v[250:251] op_sel:[0,0,1] op_sel_hi:[1,1,1]
	v_pk_fma_f32 v[246:247], v[72:73], v[172:173], v[246:247]
	v_pk_fma_f32 v[248:249], v[74:75], v[174:175], v[248:249]
	v_pk_fma_f32 v[246:247], v[76:77], v[176:177], v[246:247]
	v_pk_fma_f32 v[248:249], v[78:79], v[178:179], v[248:249]
	v_lshlrev_b32_e32 v140, 16, v229
	v_lshlrev_b32_e32 v141, 16, v228
	v_mul_f32_e32 v142, 0xbfb8aa3b, v140
	v_mul_f32_e32 v143, 0xbfb8aa3b, v141
	v_exp_f32_e32 v142, v142
	v_exp_f32_e32 v143, v143
	v_add_f32_e32 v142, 1.0, v142
	v_add_f32_e32 v143, 1.0, v143
	v_rcp_f32_e32 v142, v142
	v_rcp_f32_e32 v143, v143
	v_fma_f32 v142, v131, v142, v130
	v_mul_f32_e32 v143, v143, v141
	v_mul_f32_e32 v132, v132, v142
	ds_write2st64_b32 v134, v142, v143 offset0:2 offset1:3
	v_mov_b32_e32 v182, v143
	s_waitcnt vmcnt(8)
; __device__ __forceinline__ float bf2f(unsigned short b) { return __uint_as_float((unsigned)b << 16); }
; __device__ __forceinline__ unsigned short f2bf(float f) { unsigned u = __float_as_uint(f); u += 0x7FFFu + ((u >> 16) & 1u); return (unsigned short)(u >> 16); }
; __device__ __forceinline__ float sigm(float x) { return __builtin_amdgcn_rcpf(1.0f + __expf(-x)); }
; __device__ __forceinline__ f2 pfma(f2 a, f2 b, f2 c) { return __builtin_elementwise_fma(a, b, c); }
; __device__ __forceinline__ void hgrn_scan(const bf16_t* __restrict__ PH, int t0, int nsteps, int h, int half, int kh, int lane, float lb, f2 (&S)[32], float& cp, bf16_t* __restrict__ OHp, float* __restrict__ ckp, LAS float* L) {
;     ...
;         const float ql = bf2f(q1[0]), fz = bf2f(q1[1]), v = bf2f(q1[2]);
; #pragma unroll
;         for (int j = 0; j < 3; ++j) { q1[j] = q2[j]; q2[j] = q3[j]; }
;         { const bf16_t* r = row + (size_t)(s + 3 < nsteps ? s + 3 : nsteps - 1) * 2048; q3[0] = r[0]; q3[1] = r[512]; q3[2] = r[voff]; }
;         const float fl = lb + (1.0f - lb) * sigm(fz);
;         cp *= fl;
;         if (ckp && (s & 31) == 31 && s < 127) ckp[(s >> 5) * 128 + lane] = cp;
;         L[lane] = fl; L[64 + lane] = ql * sigm(ql);
;         f32x4 F[2][4], Q[2][4];
; #pragma unroll
;         for (int i = 0; i < 4; ++i) { F[0][i] = pf[i]; Q[0][i] = pf[16 + i]; }
;         const f2 v2 = {v, v}; f2 o2 = {0.f, 0.f}, o3 = {0.f, 0.f};
; #pragma unroll
;         for (int g = 0; g < 4; ++g) {
;             if (g < 3) {
; #pragma unroll
;                 for (int i = 0; i < 4; ++i) { F[(g + 1) & 1][i] = pf[(g + 1) * 4 + i]; Q[(g + 1) & 1][i] = pf[16 + (g + 1) * 4 + i]; } }
;             __builtin_amdgcn_sched_barrier(0);
; #pragma unroll
;             for (int i = 0; i < 4; ++i) {
;                 const f32x4 f4 = F[g & 1][i], q4 = Q[g & 1][i]; const int idx = (g * 4 + i) * 2;
;                 const f2 f01 = {f4[0], f4[1]}, f23 = {f4[2], f4[3]}, q01 = {q4[0], q4[1]}, q23 = {q4[2], q4[3]};
;                 S[idx] = pfma(f01, S[idx] - v2, v2); o2 = pfma(S[idx], q01, o2);
;                 S[idx + 1] = pfma(f23, S[idx + 1] - v2, v2); o3 = pfma(S[idx + 1], q23, o3);
;             }
;         }
;         OHp[(size_t)(t0 + s) * 512 + h * 128 + half * 64 + lane] = f2bf((o2[0] + o2[1]) + (o3[0] + o3[1]));
	v_lshlrev_b32_e32 v180, 16, v234
	v_lshlrev_b32_e32 v181, 16, v235
	v_and_b32_e32 v180, s4, v180
	v_and_b32_e32 v181, s4, v181
	v_pk_add_f32 v[252:253], v[254:255], v[180:181] neg_lo:[0,1] neg_hi:[0,1]
	ds_read_b128 v[148:151], v135 offset:128
	ds_read_b128 v[152:155], v135 offset:144
	ds_read_b128 v[156:159], v135 offset:160
	ds_read_b128 v[160:163], v135 offset:176
	ds_read_b128 v[164:167], v135 offset:384
	ds_read_b128 v[168:171], v135 offset:400
	ds_read_b128 v[172:175], v135 offset:416
	ds_read_b128 v[176:179], v135 offset:432
	v_add_f32_dpp v182, v182, v182 quad_perm:[1,0,3,2] row_mask:0xf bank_mask:0xf bound_ctrl:1
	s_waitcnt lgkmcnt(9)
	v_pk_fma_f32 v[16:17], v[192:193], v[16:17], v[250:251] op_sel_hi:[1,1,0]
	v_pk_fma_f32 v[18:19], v[194:195], v[18:19], v[250:251] op_sel_hi:[1,1,0]
	v_pk_fma_f32 v[20:21], v[196:197], v[20:21], v[250:251] op_sel_hi:[1,1,0]
	v_pk_fma_f32 v[22:23], v[198:199], v[22:23], v[250:251] op_sel_hi:[1,1,0]
	v_pk_fma_f32 v[240:241], v[16:17], v[208:209], v[240:241]
	v_pk_fma_f32 v[244:245], v[18:19], v[210:211], v[244:245]
	v_pk_fma_f32 v[240:241], v[20:21], v[212:213], v[240:241]
	v_pk_fma_f32 v[244:245], v[22:23], v[214:215], v[244:245]
	v_pk_fma_f32 v[24:25], v[200:201], v[24:25], v[250:251] op_sel_hi:[1,1,0]
	v_pk_fma_f32 v[26:27], v[202:203], v[26:27], v[250:251] op_sel_hi:[1,1,0]
	v_pk_fma_f32 v[28:29], v[204:205], v[28:29], v[250:251] op_sel_hi:[1,1,0]
	v_pk_fma_f32 v[30:31], v[206:207], v[30:31], v[250:251] op_sel_hi:[1,1,0]
	v_pk_fma_f32 v[240:241], v[24:25], v[216:217], v[240:241]
	v_pk_fma_f32 v[244:245], v[26:27], v[218:219], v[244:245]
	v_pk_fma_f32 v[240:241], v[28:29], v[220:221], v[240:241]
	v_pk_fma_f32 v[244:245], v[30:31], v[222:223], v[244:245]
	v_pk_fma_f32 v[80:81], v[192:193], v[80:81], v[250:251] op_sel:[0,0,1] op_sel_hi:[1,1,1]
	v_pk_fma_f32 v[82:83], v[194:195], v[82:83], v[250:251] op_sel:[0,0,1] op_sel_hi:[1,1,1]
	v_pk_fma_f32 v[84:85], v[196:197], v[84:85], v[250:251] op_sel:[0,0,1] op_sel_hi:[1,1,1]
	v_pk_fma_f32 v[86:87], v[198:199], v[86:87], v[250:251] op_sel:[0,0,1] op_sel_hi:[1,1,1]
	v_pk_fma_f32 v[246:247], v[80:81], v[208:209], v[246:247]
	v_pk_fma_f32 v[248:249], v[82:83], v[210:211], v[248:249]
	v_pk_fma_f32 v[246:247], v[84:85], v[212:213], v[246:247]
	v_pk_fma_f32 v[248:249], v[86:87], v[214:215], v[248:249]
	v_pk_fma_f32 v[88:89], v[200:201], v[88:89], v[250:251] op_sel:[0,0,1] op_sel_hi:[1,1,1]
	v_pk_fma_f32 v[90:91], v[202:203], v[90:91], v[250:251] op_sel:[0,0,1] op_sel_hi:[1,1,1]
	v_pk_fma_f32 v[92:93], v[204:205], v[92:93], v[250:251] op_sel:[0,0,1] op_sel_hi:[1,1,1]
	v_pk_fma_f32 v[94:95], v[206:207], v[94:95], v[250:251] op_sel:[0,0,1] op_sel_hi:[1,1,1]
	v_pk_fma_f32 v[246:247], v[88:89], v[216:217], v[246:247]
	v_pk_fma_f32 v[248:249], v[90:91], v[218:219], v[248:249]
	v_pk_fma_f32 v[246:247], v[92:93], v[220:221], v[246:247]
	v_pk_fma_f32 v[248:249], v[94:95], v[222:223], v[248:249]
	v_add_f32_dpp v182, v182, v182 quad_perm:[2,3,0,1] row_mask:0xf bank_mask:0xf bound_ctrl:1
	ds_read_b128 v[192:195], v135 offset:192
	ds_read_b128 v[196:199], v135 offset:208
	ds_read_b128 v[200:203], v135 offset:224
	ds_read_b128 v[204:207], v135 offset:240
	ds_read_b128 v[208:211], v135 offset:448
	ds_read_b128 v[212:215], v135 offset:464
	ds_read_b128 v[216:219], v135 offset:480
	ds_read_b128 v[220:223], v135 offset:496
	v_add_f32_dpp v182, v182, v182 row_half_mirror row_mask:0xf bank_mask:0xf bound_ctrl:1
	s_waitcnt lgkmcnt(8)
	v_pk_fma_f32 v[32:33], v[148:149], v[32:33], v[250:251] op_sel_hi:[1,1,0]
	v_pk_fma_f32 v[34:35], v[150:151], v[34:35], v[250:251] op_sel_hi:[1,1,0]
	v_pk_fma_f32 v[36:37], v[152:153], v[36:37], v[250:251] op_sel_hi:[1,1,0]
	v_pk_fma_f32 v[38:39], v[154:155], v[38:39], v[250:251] op_sel_hi:[1,1,0]
	v_pk_fma_f32 v[240:241], v[32:33], v[164:165], v[240:241]
	v_pk_fma_f32 v[244:245], v[34:35], v[166:167], v[244:245]
	v_pk_fma_f32 v[240:241], v[36:37], v[168:169], v[240:241]
	v_pk_fma_f32 v[244:245], v[38:39], v[170:171], v[244:245]
	v_pk_fma_f32 v[40:41], v[156:157], v[40:41], v[250:251] op_sel_hi:[1,1,0]
	v_pk_fma_f32 v[42:43], v[158:159], v[42:43], v[250:251] op_sel_hi:[1,1,0]
	v_pk_fma_f32 v[44:45], v[160:161], v[44:45], v[250:251] op_sel_hi:[1,1,0]
	v_pk_fma_f32 v[46:47], v[162:163], v[46:47], v[250:251] op_sel_hi:[1,1,0]
	v_pk_fma_f32 v[240:241], v[40:41], v[172:173], v[240:241]
	v_pk_fma_f32 v[244:245], v[42:43], v[174:175], v[244:245]
	v_pk_fma_f32 v[240:241], v[44:45], v[176:177], v[240:241]
	v_pk_fma_f32 v[244:245], v[46:47], v[178:179], v[244:245]
	v_pk_fma_f32 v[96:97], v[148:149], v[96:97], v[250:251] op_sel:[0,0,1] op_sel_hi:[1,1,1]
	v_pk_fma_f32 v[98:99], v[150:151], v[98:99], v[250:251] op_sel:[0,0,1] op_sel_hi:[1,1,1]
	v_pk_fma_f32 v[100:101], v[152:153], v[100:101], v[250:251] op_sel:[0,0,1] op_sel_hi:[1,1,1]
	v_pk_fma_f32 v[102:103], v[154:155], v[102:103], v[250:251] op_sel:[0,0,1] op_sel_hi:[1,1,1]
	v_pk_fma_f32 v[246:247], v[96:97], v[164:165], v[246:247]
	v_pk_fma_f32 v[248:249], v[98:99], v[166:167], v[248:249]
	v_pk_fma_f32 v[246:247], v[100:101], v[168:169], v[246:247]
	v_pk_fma_f32 v[248:249], v[102:103], v[170:171], v[248:249]
	v_pk_fma_f32 v[104:105], v[156:157], v[104:105], v[250:251] op_sel:[0,0,1] op_sel_hi:[1,1,1]
	v_pk_fma_f32 v[106:107], v[158:159], v[106:107], v[250:251] op_sel:[0,0,1] op_sel_hi:[1,1,1]
	v_pk_fma_f32 v[108:109], v[160:161], v[108:109], v[250:251] op_sel:[0,0,1] op_sel_hi:[1,1,1]
	v_pk_fma_f32 v[110:111], v[162:163], v[110:111], v[250:251] op_sel:[0,0,1] op_sel_hi:[1,1,1]
	v_pk_fma_f32 v[246:247], v[104:105], v[172:173], v[246:247]
	v_pk_fma_f32 v[248:249], v[106:107], v[174:175], v[248:249]
	v_pk_fma_f32 v[246:247], v[108:109], v[176:177], v[246:247]
	v_pk_fma_f32 v[248:249], v[110:111], v[178:179], v[248:249]
	v_add_f32_dpp v182, v182, v182 row_mirror row_mask:0xf bank_mask:0xf bound_ctrl:1
	ds_read_b128 v[148:151], v135 offset:512
	ds_read_b128 v[152:155], v135 offset:528
	ds_read_b128 v[156:159], v135 offset:544
	ds_read_b128 v[160:163], v135 offset:560
	ds_read_b128 v[164:167], v135 offset:768
	ds_read_b128 v[168:171], v135 offset:784
	ds_read_b128 v[172:175], v135 offset:800
	ds_read_b128 v[176:179], v135 offset:816
	v_readlane_b32 s0, v182, 0
	v_readlane_b32 s1, v182, 16
	v_readlane_b32 s6, v182, 32
	v_readlane_b32 s7, v182, 48
	s_waitcnt lgkmcnt(8)
; __device__ __forceinline__ float bf2f(unsigned short b) { return __uint_as_float((unsigned)b << 16); }
; __device__ __forceinline__ unsigned short f2bf(float f) { unsigned u = __float_as_uint(f); u += 0x7FFFu + ((u >> 16) & 1u); return (unsigned short)(u >> 16); }
; __device__ __forceinline__ float sigm(float x) { return __builtin_amdgcn_rcpf(1.0f + __expf(-x)); }
; __device__ __forceinline__ f2 pfma(f2 a, f2 b, f2 c) { return __builtin_elementwise_fma(a, b, c); }
; __device__ __forceinline__ void hgrn_scan(const bf16_t* __restrict__ PH, int t0, int nsteps, int h, int half, int kh, int lane, float lb, f2 (&S)[32], float& cp, bf16_t* __restrict__ OHp, float* __restrict__ ckp, LAS float* L) {
;     ...
;         const float ql = bf2f(q1[0]), fz = bf2f(q1[1]), v = bf2f(q1[2]);
; #pragma unroll
;         for (int j = 0; j < 3; ++j) { q1[j] = q2[j]; q2[j] = q3[j]; }
;         { const bf16_t* r = row + (size_t)(s + 3 < nsteps ? s + 3 : nsteps - 1) * 2048; q3[0] = r[0]; q3[1] = r[512]; q3[2] = r[voff]; }
;         const float fl = lb + (1.0f - lb) * sigm(fz);
;         cp *= fl;
;         if (ckp && (s & 31) == 31 && s < 127) ckp[(s >> 5) * 128 + lane] = cp;
;         L[lane] = fl; L[64 + lane] = ql * sigm(ql);
;         f32x4 F[2][4], Q[2][4];
; #pragma unroll
;         for (int i = 0; i < 4; ++i) { F[0][i] = pf[i]; Q[0][i] = pf[16 + i]; }
;         const f2 v2 = {v, v}; f2 o2 = {0.f, 0.f}, o3 = {0.f, 0.f};
; #pragma unroll
;         for (int g = 0; g < 4; ++g) {
;             if (g < 3) {
; #pragma unroll
;                 for (int i = 0; i < 4; ++i) { F[(g + 1) & 1][i] = pf[(g + 1) * 4 + i]; Q[(g + 1) & 1][i] = pf[16 + (g + 1) * 4 + i]; } }
;             __builtin_amdgcn_sched_barrier(0);
; #pragma unroll
;             for (int i = 0; i < 4; ++i) {
;                 const f32x4 f4 = F[g & 1][i], q4 = Q[g & 1][i]; const int idx = (g * 4 + i) * 2;
;                 const f2 f01 = {f4[0], f4[1]}, f23 = {f4[2], f4[3]}, q01 = {q4[0], q4[1]}, q23 = {q4[2], q4[3]};
;                 S[idx] = pfma(f01, S[idx] - v2, v2); o2 = pfma(S[idx], q01, o2);
;                 S[idx + 1] = pfma(f23, S[idx + 1] - v2, v2); o3 = pfma(S[idx + 1], q23, o3);
;             }
;         }
;         OHp[(size_t)(t0 + s) * 512 + h * 128 + half * 64 + lane] = f2bf((o2[0] + o2[1]) + (o3[0] + o3[1]));
	v_pk_fma_f32 v[48:49], v[192:193], v[48:49], v[250:251] op_sel_hi:[1,1,0]
	v_pk_fma_f32 v[50:51], v[194:195], v[50:51], v[250:251] op_sel_hi:[1,1,0]
	v_pk_fma_f32 v[52:53], v[196:197], v[52:53], v[250:251] op_sel_hi:[1,1,0]
	v_pk_fma_f32 v[54:55], v[198:199], v[54:55], v[250:251] op_sel_hi:[1,1,0]
	v_pk_fma_f32 v[240:241], v[48:49], v[208:209], v[240:241]
	v_pk_fma_f32 v[244:245], v[50:51], v[210:211], v[244:245]
	v_pk_fma_f32 v[240:241], v[52:53], v[212:213], v[240:241]
	v_pk_fma_f32 v[244:245], v[54:55], v[214:215], v[244:245]
	v_pk_fma_f32 v[56:57], v[200:201], v[56:57], v[250:251] op_sel_hi:[1,1,0]
	v_pk_fma_f32 v[58:59], v[202:203], v[58:59], v[250:251] op_sel_hi:[1,1,0]
	v_pk_fma_f32 v[60:61], v[204:205], v[60:61], v[250:251] op_sel_hi:[1,1,0]
	v_pk_fma_f32 v[62:63], v[206:207], v[62:63], v[250:251] op_sel_hi:[1,1,0]
	v_pk_fma_f32 v[240:241], v[56:57], v[216:217], v[240:241]
	v_pk_fma_f32 v[244:245], v[58:59], v[218:219], v[244:245]
	v_pk_fma_f32 v[240:241], v[60:61], v[220:221], v[240:241]
	v_pk_fma_f32 v[244:245], v[62:63], v[222:223], v[244:245]
	v_pk_fma_f32 v[112:113], v[192:193], v[112:113], v[250:251] op_sel:[0,0,1] op_sel_hi:[1,1,1]
	v_pk_fma_f32 v[114:115], v[194:195], v[114:115], v[250:251] op_sel:[0,0,1] op_sel_hi:[1,1,1]
	v_pk_fma_f32 v[116:117], v[196:197], v[116:117], v[250:251] op_sel:[0,0,1] op_sel_hi:[1,1,1]
	v_pk_fma_f32 v[118:119], v[198:199], v[118:119], v[250:251] op_sel:[0,0,1] op_sel_hi:[1,1,1]
	v_pk_fma_f32 v[246:247], v[112:113], v[208:209], v[246:247]
	v_pk_fma_f32 v[248:249], v[114:115], v[210:211], v[248:249]
	v_pk_fma_f32 v[246:247], v[116:117], v[212:213], v[246:247]
	v_pk_fma_f32 v[248:249], v[118:119], v[214:215], v[248:249]
	v_pk_fma_f32 v[120:121], v[200:201], v[120:121], v[250:251] op_sel:[0,0,1] op_sel_hi:[1,1,1]
	v_pk_fma_f32 v[122:123], v[202:203], v[122:123], v[250:251] op_sel:[0,0,1] op_sel_hi:[1,1,1]
	v_pk_fma_f32 v[124:125], v[204:205], v[124:125], v[250:251] op_sel:[0,0,1] op_sel_hi:[1,1,1]
	v_pk_fma_f32 v[126:127], v[206:207], v[126:127], v[250:251] op_sel:[0,0,1] op_sel_hi:[1,1,1]
	v_pk_fma_f32 v[246:247], v[120:121], v[216:217], v[246:247]
	v_pk_fma_f32 v[248:249], v[122:123], v[218:219], v[248:249]
	v_pk_fma_f32 v[246:247], v[124:125], v[220:221], v[246:247]
	v_pk_fma_f32 v[248:249], v[126:127], v[222:223], v[248:249]
	v_mov_b32_e32 v183, s0
	v_add_f32_e32 v183, s1, v183
	v_add_f32_e32 v183, s6, v183
	v_add_f32_e32 v183, s7, v183
	v_add_f32_e32 v240, v240, v241
	v_add_f32_e32 v244, v244, v245
	v_add_f32_e32 v240, v240, v244
	v_fmac_f32_e32 v240, s2, v254
	v_bfe_u32 v244, v240, 16, 1
	v_add3_u32 v240, v240, v244, s69
	global_store_short_d16_hi v138, v240, s[26:27]
	v_add_f32_e32 v246, v246, v247
	v_add_f32_e32 v248, v248, v249
	v_add_f32_e32 v246, v246, v248
	v_fmac_f32_e32 v246, s2, v255
	v_bfe_u32 v248, v246, 16, 1
	v_add3_u32 v246, v246, v248, s69
	global_store_short_d16_hi v138, v246, s[26:27] offset:128
	v_readfirstlane_b32 s2, v183
	v_mov_b64_e32 v[250:251], v[252:253]
	v_mov_b64_e32 v[254:255], v[180:181]
	v_add_u32_e32 v138, 0x400, v138
	global_load_ushort v228, v136, s[24:25]
	global_load_ushort v229, v136, s[24:25] offset:1024
	global_load_ushort v230, v137, s[24:25]
	global_load_ushort v231, v137, s[24:25] offset:128
	v_add_u32_e32 v136, 0x1000, v136
	v_add_u32_e32 v137, 0x1000, v137
	ds_read_b128 v[192:195], v135 offset:576
	ds_read_b128 v[196:199], v135 offset:592
	ds_read_b128 v[200:203], v135 offset:608
	ds_read_b128 v[204:207], v135 offset:624
	ds_read_b128 v[208:211], v135 offset:832
	ds_read_b128 v[212:215], v135 offset:848
	ds_read_b128 v[216:219], v135 offset:864
	ds_read_b128 v[220:223], v135 offset:880
	s_waitcnt lgkmcnt(8)
	v_pk_fma_f32 v[0:1], v[148:149], v[0:1], v[250:251] op_sel_hi:[1,1,0]
	v_pk_fma_f32 v[2:3], v[150:151], v[2:3], v[250:251] op_sel_hi:[1,1,0]
	v_pk_fma_f32 v[4:5], v[152:153], v[4:5], v[250:251] op_sel_hi:[1,1,0]
	v_pk_fma_f32 v[6:7], v[154:155], v[6:7], v[250:251] op_sel_hi:[1,1,0]
	v_pk_fma_f32 v[240:241], v[0:1], v[164:165], 0 op_sel_hi:[1,1,0]
	v_pk_fma_f32 v[244:245], v[2:3], v[166:167], 0 op_sel_hi:[1,1,0]
	v_pk_fma_f32 v[240:241], v[4:5], v[168:169], v[240:241]
	v_pk_fma_f32 v[244:245], v[6:7], v[170:171], v[244:245]
	v_pk_fma_f32 v[8:9], v[156:157], v[8:9], v[250:251] op_sel_hi:[1,1,0]
	v_pk_fma_f32 v[10:11], v[158:159], v[10:11], v[250:251] op_sel_hi:[1,1,0]
	v_pk_fma_f32 v[12:13], v[160:161], v[12:13], v[250:251] op_sel_hi:[1,1,0]
	v_pk_fma_f32 v[14:15], v[162:163], v[14:15], v[250:251] op_sel_hi:[1,1,0]
	v_pk_fma_f32 v[240:241], v[8:9], v[172:173], v[240:241]
	v_pk_fma_f32 v[244:245], v[10:11], v[174:175], v[244:245]
	v_pk_fma_f32 v[240:241], v[12:13], v[176:177], v[240:241]
	v_pk_fma_f32 v[244:245], v[14:15], v[178:179], v[244:245]
	v_pk_fma_f32 v[64:65], v[148:149], v[64:65], v[250:251] op_sel:[0,0,1] op_sel_hi:[1,1,1]
	v_pk_fma_f32 v[66:67], v[150:151], v[66:67], v[250:251] op_sel:[0,0,1] op_sel_hi:[1,1,1]
	v_pk_fma_f32 v[68:69], v[152:153], v[68:69], v[250:251] op_sel:[0,0,1] op_sel_hi:[1,1,1]
	v_pk_fma_f32 v[70:71], v[154:155], v[70:71], v[250:251] op_sel:[0,0,1] op_sel_hi:[1,1,1]
	v_pk_fma_f32 v[246:247], v[64:65], v[164:165], 0 op_sel_hi:[1,1,0]
	v_pk_fma_f32 v[248:249], v[66:67], v[166:167], 0 op_sel_hi:[1,1,0]
	v_pk_fma_f32 v[246:247], v[68:69], v[168:169], v[246:247]
	v_pk_fma_f32 v[248:249], v[70:71], v[170:171], v[248:249]
	v_pk_fma_f32 v[72:73], v[156:157], v[72:73], v[250:251] op_sel:[0,0,1] op_sel_hi:[1,1,1]
	v_pk_fma_f32 v[74:75], v[158:159], v[74:75], v[250:251] op_sel:[0,0,1] op_sel_hi:[1,1,1]
	v_pk_fma_f32 v[76:77], v[160:161], v[76:77], v[250:251] op_sel:[0,0,1] op_sel_hi:[1,1,1]
	v_pk_fma_f32 v[78:79], v[162:163], v[78:79], v[250:251] op_sel:[0,0,1] op_sel_hi:[1,1,1]
	v_pk_fma_f32 v[246:247], v[72:73], v[172:173], v[246:247]
	v_pk_fma_f32 v[248:249], v[74:75], v[174:175], v[248:249]
	v_pk_fma_f32 v[246:247], v[76:77], v[176:177], v[246:247]
	v_pk_fma_f32 v[248:249], v[78:79], v[178:179], v[248:249]
	v_lshlrev_b32_e32 v140, 16, v233
	v_lshlrev_b32_e32 v141, 16, v232
	v_mul_f32_e32 v142, 0xbfb8aa3b, v140
	v_mul_f32_e32 v143, 0xbfb8aa3b, v141
	v_exp_f32_e32 v142, v142
	v_exp_f32_e32 v143, v143
	v_add_f32_e32 v142, 1.0, v142
	v_add_f32_e32 v143, 1.0, v143
	v_rcp_f32_e32 v142, v142
	v_rcp_f32_e32 v143, v143
	v_fma_f32 v142, v131, v142, v130
	v_mul_f32_e32 v143, v143, v141
	v_mul_f32_e32 v132, v132, v142
	ds_write2st64_b32 v134, v142, v143 offset0:0 offset1:1
	v_mov_b32_e32 v182, v143
	s_waitcnt vmcnt(10)
; __device__ __forceinline__ float bf2f(unsigned short b) { return __uint_as_float((unsigned)b << 16); }
; __device__ __forceinline__ unsigned short f2bf(float f) { unsigned u = __float_as_uint(f); u += 0x7FFFu + ((u >> 16) & 1u); return (unsigned short)(u >> 16); }
; __device__ __forceinline__ float sigm(float x) { return __builtin_amdgcn_rcpf(1.0f + __expf(-x)); }
; __device__ __forceinline__ f2 pfma(f2 a, f2 b, f2 c) { return __builtin_elementwise_fma(a, b, c); }
; __device__ __forceinline__ void hgrn_scan(const bf16_t* __restrict__ PH, int t0, int nsteps, int h, int half, int kh, int lane, float lb, f2 (&S)[32], float& cp, bf16_t* __restrict__ OHp, float* __restrict__ ckp, LAS float* L) {
;     ...
;         const float ql = bf2f(q1[0]), fz = bf2f(q1[1]), v = bf2f(q1[2]);
; #pragma unroll
;         for (int j = 0; j < 3; ++j) { q1[j] = q2[j]; q2[j] = q3[j]; }
;         { const bf16_t* r = row + (size_t)(s + 3 < nsteps ? s + 3 : nsteps - 1) * 2048; q3[0] = r[0]; q3[1] = r[512]; q3[2] = r[voff]; }
;         const float fl = lb + (1.0f - lb) * sigm(fz);
;         cp *= fl;
;         if (ckp && (s & 31) == 31 && s < 127) ckp[(s >> 5) * 128 + lane] = cp;
;         L[lane] = fl; L[64 + lane] = ql * sigm(ql);
;         f32x4 F[2][4], Q[2][4];
; #pragma unroll
;         for (int i = 0; i < 4; ++i) { F[0][i] = pf[i]; Q[0][i] = pf[16 + i]; }
;         const f2 v2 = {v, v}; f2 o2 = {0.f, 0.f}, o3 = {0.f, 0.f};
; #pragma unroll
;         for (int g = 0; g < 4; ++g) {
;             if (g < 3) {
; #pragma unroll
;                 for (int i = 0; i < 4; ++i) { F[(g + 1) & 1][i] = pf[(g + 1) * 4 + i]; Q[(g + 1) & 1][i] = pf[16 + (g + 1) * 4 + i]; } }
;             __builtin_amdgcn_sched_barrier(0);
; #pragma unroll
;             for (int i = 0; i < 4; ++i) {
;                 const f32x4 f4 = F[g & 1][i], q4 = Q[g & 1][i]; const int idx = (g * 4 + i) * 2;
;                 const f2 f01 = {f4[0], f4[1]}, f23 = {f4[2], f4[3]}, q01 = {q4[0], q4[1]}, q23 = {q4[2], q4[3]};
;                 S[idx] = pfma(f01, S[idx] - v2, v2); o2 = pfma(S[idx], q01, o2);
;                 S[idx + 1] = pfma(f23, S[idx + 1] - v2, v2); o3 = pfma(S[idx + 1], q23, o3);
;             }
;         }
;         OHp[(size_t)(t0 + s) * 512 + h * 128 + half * 64 + lane] = f2bf((o2[0] + o2[1]) + (o3[0] + o3[1]));
	v_lshlrev_b32_e32 v180, 16, v238
	v_lshlrev_b32_e32 v181, 16, v239
	v_and_b32_e32 v180, s4, v180
	v_and_b32_e32 v181, s4, v181
	v_pk_add_f32 v[252:253], v[254:255], v[180:181] neg_lo:[0,1] neg_hi:[0,1]
	ds_read_b128 v[148:151], v135 offset:640
	ds_read_b128 v[152:155], v135 offset:656
	ds_read_b128 v[156:159], v135 offset:672
	ds_read_b128 v[160:163], v135 offset:688
	ds_read_b128 v[164:167], v135 offset:896
	ds_read_b128 v[168:171], v135 offset:912
	ds_read_b128 v[172:175], v135 offset:928
	ds_read_b128 v[176:179], v135 offset:944
	v_add_f32_dpp v182, v182, v182 quad_perm:[1,0,3,2] row_mask:0xf bank_mask:0xf bound_ctrl:1
	s_waitcnt lgkmcnt(9)
	v_pk_fma_f32 v[16:17], v[192:193], v[16:17], v[250:251] op_sel_hi:[1,1,0]
	v_pk_fma_f32 v[18:19], v[194:195], v[18:19], v[250:251] op_sel_hi:[1,1,0]
	v_pk_fma_f32 v[20:21], v[196:197], v[20:21], v[250:251] op_sel_hi:[1,1,0]
	v_pk_fma_f32 v[22:23], v[198:199], v[22:23], v[250:251] op_sel_hi:[1,1,0]
	v_pk_fma_f32 v[240:241], v[16:17], v[208:209], v[240:241]
	v_pk_fma_f32 v[244:245], v[18:19], v[210:211], v[244:245]
	v_pk_fma_f32 v[240:241], v[20:21], v[212:213], v[240:241]
	v_pk_fma_f32 v[244:245], v[22:23], v[214:215], v[244:245]
	v_pk_fma_f32 v[24:25], v[200:201], v[24:25], v[250:251] op_sel_hi:[1,1,0]
	v_pk_fma_f32 v[26:27], v[202:203], v[26:27], v[250:251] op_sel_hi:[1,1,0]
	v_pk_fma_f32 v[28:29], v[204:205], v[28:29], v[250:251] op_sel_hi:[1,1,0]
	v_pk_fma_f32 v[30:31], v[206:207], v[30:31], v[250:251] op_sel_hi:[1,1,0]
	v_pk_fma_f32 v[240:241], v[24:25], v[216:217], v[240:241]
	v_pk_fma_f32 v[244:245], v[26:27], v[218:219], v[244:245]
	v_pk_fma_f32 v[240:241], v[28:29], v[220:221], v[240:241]
	v_pk_fma_f32 v[244:245], v[30:31], v[222:223], v[244:245]
	v_pk_fma_f32 v[80:81], v[192:193], v[80:81], v[250:251] op_sel:[0,0,1] op_sel_hi:[1,1,1]
	v_pk_fma_f32 v[82:83], v[194:195], v[82:83], v[250:251] op_sel:[0,0,1] op_sel_hi:[1,1,1]
	v_pk_fma_f32 v[84:85], v[196:197], v[84:85], v[250:251] op_sel:[0,0,1] op_sel_hi:[1,1,1]
	v_pk_fma_f32 v[86:87], v[198:199], v[86:87], v[250:251] op_sel:[0,0,1] op_sel_hi:[1,1,1]
	v_pk_fma_f32 v[246:247], v[80:81], v[208:209], v[246:247]
	v_pk_fma_f32 v[248:249], v[82:83], v[210:211], v[248:249]
	v_pk_fma_f32 v[246:247], v[84:85], v[212:213], v[246:247]
	v_pk_fma_f32 v[248:249], v[86:87], v[214:215], v[248:249]
	v_pk_fma_f32 v[88:89], v[200:201], v[88:89], v[250:251] op_sel:[0,0,1] op_sel_hi:[1,1,1]
	v_pk_fma_f32 v[90:91], v[202:203], v[90:91], v[250:251] op_sel:[0,0,1] op_sel_hi:[1,1,1]
	v_pk_fma_f32 v[92:93], v[204:205], v[92:93], v[250:251] op_sel:[0,0,1] op_sel_hi:[1,1,1]
	v_pk_fma_f32 v[94:95], v[206:207], v[94:95], v[250:251] op_sel:[0,0,1] op_sel_hi:[1,1,1]
	v_pk_fma_f32 v[246:247], v[88:89], v[216:217], v[246:247]
	v_pk_fma_f32 v[248:249], v[90:91], v[218:219], v[248:249]
	v_pk_fma_f32 v[246:247], v[92:93], v[220:221], v[246:247]
	v_pk_fma_f32 v[248:249], v[94:95], v[222:223], v[248:249]
	v_add_f32_dpp v182, v182, v182 quad_perm:[2,3,0,1] row_mask:0xf bank_mask:0xf bound_ctrl:1
	ds_read_b128 v[192:195], v135 offset:704
	ds_read_b128 v[196:199], v135 offset:720
	ds_read_b128 v[200:203], v135 offset:736
	ds_read_b128 v[204:207], v135 offset:752
	ds_read_b128 v[208:211], v135 offset:960
	ds_read_b128 v[212:215], v135 offset:976
	ds_read_b128 v[216:219], v135 offset:992
	ds_read_b128 v[220:223], v135 offset:1008
	v_add_f32_dpp v182, v182, v182 row_half_mirror row_mask:0xf bank_mask:0xf bound_ctrl:1
	s_waitcnt lgkmcnt(8)
	v_pk_fma_f32 v[32:33], v[148:149], v[32:33], v[250:251] op_sel_hi:[1,1,0]
	v_pk_fma_f32 v[34:35], v[150:151], v[34:35], v[250:251] op_sel_hi:[1,1,0]
	v_pk_fma_f32 v[36:37], v[152:153], v[36:37], v[250:251] op_sel_hi:[1,1,0]
	v_pk_fma_f32 v[38:39], v[154:155], v[38:39], v[250:251] op_sel_hi:[1,1,0]
	v_pk_fma_f32 v[240:241], v[32:33], v[164:165], v[240:241]
	v_pk_fma_f32 v[244:245], v[34:35], v[166:167], v[244:245]
	v_pk_fma_f32 v[240:241], v[36:37], v[168:169], v[240:241]
	v_pk_fma_f32 v[244:245], v[38:39], v[170:171], v[244:245]
	v_pk_fma_f32 v[40:41], v[156:157], v[40:41], v[250:251] op_sel_hi:[1,1,0]
	v_pk_fma_f32 v[42:43], v[158:159], v[42:43], v[250:251] op_sel_hi:[1,1,0]
	v_pk_fma_f32 v[44:45], v[160:161], v[44:45], v[250:251] op_sel_hi:[1,1,0]
	v_pk_fma_f32 v[46:47], v[162:163], v[46:47], v[250:251] op_sel_hi:[1,1,0]
	v_pk_fma_f32 v[240:241], v[40:41], v[172:173], v[240:241]
	v_pk_fma_f32 v[244:245], v[42:43], v[174:175], v[244:245]
	v_pk_fma_f32 v[240:241], v[44:45], v[176:177], v[240:241]
	v_pk_fma_f32 v[244:245], v[46:47], v[178:179], v[244:245]
	v_pk_fma_f32 v[96:97], v[148:149], v[96:97], v[250:251] op_sel:[0,0,1] op_sel_hi:[1,1,1]
	v_pk_fma_f32 v[98:99], v[150:151], v[98:99], v[250:251] op_sel:[0,0,1] op_sel_hi:[1,1,1]
	v_pk_fma_f32 v[100:101], v[152:153], v[100:101], v[250:251] op_sel:[0,0,1] op_sel_hi:[1,1,1]
	v_pk_fma_f32 v[102:103], v[154:155], v[102:103], v[250:251] op_sel:[0,0,1] op_sel_hi:[1,1,1]
	v_pk_fma_f32 v[246:247], v[96:97], v[164:165], v[246:247]
	v_pk_fma_f32 v[248:249], v[98:99], v[166:167], v[248:249]
	v_pk_fma_f32 v[246:247], v[100:101], v[168:169], v[246:247]
	v_pk_fma_f32 v[248:249], v[102:103], v[170:171], v[248:249]
	v_pk_fma_f32 v[104:105], v[156:157], v[104:105], v[250:251] op_sel:[0,0,1] op_sel_hi:[1,1,1]
	v_pk_fma_f32 v[106:107], v[158:159], v[106:107], v[250:251] op_sel:[0,0,1] op_sel_hi:[1,1,1]
	v_pk_fma_f32 v[108:109], v[160:161], v[108:109], v[250:251] op_sel:[0,0,1] op_sel_hi:[1,1,1]
	v_pk_fma_f32 v[110:111], v[162:163], v[110:111], v[250:251] op_sel:[0,0,1] op_sel_hi:[1,1,1]
	v_pk_fma_f32 v[246:247], v[104:105], v[172:173], v[246:247]
	v_pk_fma_f32 v[248:249], v[106:107], v[174:175], v[248:249]
	v_pk_fma_f32 v[246:247], v[108:109], v[176:177], v[246:247]
	v_pk_fma_f32 v[248:249], v[110:111], v[178:179], v[248:249]
	v_add_f32_dpp v182, v182, v182 row_mirror row_mask:0xf bank_mask:0xf bound_ctrl:1
	ds_read_b128 v[148:151], v135 offset:0
	ds_read_b128 v[152:155], v135 offset:16
	ds_read_b128 v[156:159], v135 offset:32
	ds_read_b128 v[160:163], v135 offset:48
	ds_read_b128 v[164:167], v135 offset:256
	ds_read_b128 v[168:171], v135 offset:272
	ds_read_b128 v[172:175], v135 offset:288
	ds_read_b128 v[176:179], v135 offset:304
	v_readlane_b32 s0, v182, 0
	v_readlane_b32 s1, v182, 16
	v_readlane_b32 s6, v182, 32
	v_readlane_b32 s7, v182, 48
	s_waitcnt lgkmcnt(8)
; __device__ __forceinline__ float bf2f(unsigned short b) { return __uint_as_float((unsigned)b << 16); }
; __device__ __forceinline__ unsigned short f2bf(float f) { unsigned u = __float_as_uint(f); u += 0x7FFFu + ((u >> 16) & 1u); return (unsigned short)(u >> 16); }
; __device__ __forceinline__ float sigm(float x) { return __builtin_amdgcn_rcpf(1.0f + __expf(-x)); }
; __device__ __forceinline__ f2 pfma(f2 a, f2 b, f2 c) { return __builtin_elementwise_fma(a, b, c); }
; __device__ __forceinline__ void hgrn_scan(const bf16_t* __restrict__ PH, int t0, int nsteps, int h, int half, int kh, int lane, float lb, f2 (&S)[32], float& cp, bf16_t* __restrict__ OHp, float* __restrict__ ckp, LAS float* L) {
;     ...
;         const float ql = bf2f(q1[0]), fz = bf2f(q1[1]), v = bf2f(q1[2]);
; #pragma unroll
;         for (int j = 0; j < 3; ++j) { q1[j] = q2[j]; q2[j] = q3[j]; }
;         { const bf16_t* r = row + (size_t)(s + 3 < nsteps ? s + 3 : nsteps - 1) * 2048; q3[0] = r[0]; q3[1] = r[512]; q3[2] = r[voff]; }
;         const float fl = lb + (1.0f - lb) * sigm(fz);
;         cp *= fl;
;         if (ckp && (s & 31) == 31 && s < 127) ckp[(s >> 5) * 128 + lane] = cp;
;         L[lane] = fl; L[64 + lane] = ql * sigm(ql);
;         f32x4 F[2][4], Q[2][4];
; #pragma unroll
;         for (int i = 0; i < 4; ++i) { F[0][i] = pf[i]; Q[0][i] = pf[16 + i]; }
;         const f2 v2 = {v, v}; f2 o2 = {0.f, 0.f}, o3 = {0.f, 0.f};
; #pragma unroll
;         for (int g = 0; g < 4; ++g) {
;             if (g < 3) {
; #pragma unroll
;                 for (int i = 0; i < 4; ++i) { F[(g + 1) & 1][i] = pf[(g + 1) * 4 + i]; Q[(g + 1) & 1][i] = pf[16 + (g + 1) * 4 + i]; } }
;             __builtin_amdgcn_sched_barrier(0);
; #pragma unroll
;             for (int i = 0; i < 4; ++i) {
;                 const f32x4 f4 = F[g & 1][i], q4 = Q[g & 1][i]; const int idx = (g * 4 + i) * 2;
;                 const f2 f01 = {f4[0], f4[1]}, f23 = {f4[2], f4[3]}, q01 = {q4[0], q4[1]}, q23 = {q4[2], q4[3]};
;                 S[idx] = pfma(f01, S[idx] - v2, v2); o2 = pfma(S[idx], q01, o2);
;                 S[idx + 1] = pfma(f23, S[idx + 1] - v2, v2); o3 = pfma(S[idx + 1], q23, o3);
;             }
;         }
;         OHp[(size_t)(t0 + s) * 512 + h * 128 + half * 64 + lane] = f2bf((o2[0] + o2[1]) + (o3[0] + o3[1]));
	v_pk_fma_f32 v[48:49], v[192:193], v[48:49], v[250:251] op_sel_hi:[1,1,0]
	v_pk_fma_f32 v[50:51], v[194:195], v[50:51], v[250:251] op_sel_hi:[1,1,0]
	v_pk_fma_f32 v[52:53], v[196:197], v[52:53], v[250:251] op_sel_hi:[1,1,0]
	v_pk_fma_f32 v[54:55], v[198:199], v[54:55], v[250:251] op_sel_hi:[1,1,0]
	v_pk_fma_f32 v[240:241], v[48:49], v[208:209], v[240:241]
	v_pk_fma_f32 v[244:245], v[50:51], v[210:211], v[244:245]
	v_pk_fma_f32 v[240:241], v[52:53], v[212:213], v[240:241]
	v_pk_fma_f32 v[244:245], v[54:55], v[214:215], v[244:245]
	v_pk_fma_f32 v[56:57], v[200:201], v[56:57], v[250:251] op_sel_hi:[1,1,0]
	v_pk_fma_f32 v[58:59], v[202:203], v[58:59], v[250:251] op_sel_hi:[1,1,0]
	v_pk_fma_f32 v[60:61], v[204:205], v[60:61], v[250:251] op_sel_hi:[1,1,0]
	v_pk_fma_f32 v[62:63], v[206:207], v[62:63], v[250:251] op_sel_hi:[1,1,0]
	v_pk_fma_f32 v[240:241], v[56:57], v[216:217], v[240:241]
	v_pk_fma_f32 v[244:245], v[58:59], v[218:219], v[244:245]
	v_pk_fma_f32 v[240:241], v[60:61], v[220:221], v[240:241]
	v_pk_fma_f32 v[244:245], v[62:63], v[222:223], v[244:245]
	v_pk_fma_f32 v[112:113], v[192:193], v[112:113], v[250:251] op_sel:[0,0,1] op_sel_hi:[1,1,1]
	v_pk_fma_f32 v[114:115], v[194:195], v[114:115], v[250:251] op_sel:[0,0,1] op_sel_hi:[1,1,1]
	v_pk_fma_f32 v[116:117], v[196:197], v[116:117], v[250:251] op_sel:[0,0,1] op_sel_hi:[1,1,1]
	v_pk_fma_f32 v[118:119], v[198:199], v[118:119], v[250:251] op_sel:[0,0,1] op_sel_hi:[1,1,1]
	v_pk_fma_f32 v[246:247], v[112:113], v[208:209], v[246:247]
	v_pk_fma_f32 v[248:249], v[114:115], v[210:211], v[248:249]
	v_pk_fma_f32 v[246:247], v[116:117], v[212:213], v[246:247]
	v_pk_fma_f32 v[248:249], v[118:119], v[214:215], v[248:249]
	v_pk_fma_f32 v[120:121], v[200:201], v[120:121], v[250:251] op_sel:[0,0,1] op_sel_hi:[1,1,1]
	v_pk_fma_f32 v[122:123], v[202:203], v[122:123], v[250:251] op_sel:[0,0,1] op_sel_hi:[1,1,1]
	v_pk_fma_f32 v[124:125], v[204:205], v[124:125], v[250:251] op_sel:[0,0,1] op_sel_hi:[1,1,1]
	v_pk_fma_f32 v[126:127], v[206:207], v[126:127], v[250:251] op_sel:[0,0,1] op_sel_hi:[1,1,1]
	v_pk_fma_f32 v[246:247], v[120:121], v[216:217], v[246:247]
	v_pk_fma_f32 v[248:249], v[122:123], v[218:219], v[248:249]
	v_pk_fma_f32 v[246:247], v[124:125], v[220:221], v[246:247]
	v_pk_fma_f32 v[248:249], v[126:127], v[222:223], v[248:249]
	v_mov_b32_e32 v183, s0
	v_add_f32_e32 v183, s1, v183
	v_add_f32_e32 v183, s6, v183
	v_add_f32_e32 v183, s7, v183
	v_add_f32_e32 v240, v240, v241
	v_add_f32_e32 v244, v244, v245
	v_add_f32_e32 v240, v240, v244
	v_fmac_f32_e32 v240, s2, v254
	v_bfe_u32 v244, v240, 16, 1
	v_add3_u32 v240, v240, v244, s69
	global_store_short_d16_hi v138, v240, s[26:27]
	v_add_f32_e32 v246, v246, v247
	v_add_f32_e32 v248, v248, v249
	v_add_f32_e32 v246, v246, v248
	v_fmac_f32_e32 v246, s2, v255
	v_bfe_u32 v248, v246, 16, 1
	v_add3_u32 v246, v246, v248, s69
	global_store_short_d16_hi v138, v246, s[26:27] offset:128
	v_readfirstlane_b32 s2, v183
	v_mov_b64_e32 v[250:251], v[252:253]
	v_mov_b64_e32 v[254:255], v[180:181]
	v_add_u32_e32 v138, 0x400, v138
	global_load_ushort v232, v136, s[24:25]
	global_load_ushort v233, v136, s[24:25] offset:1024
	global_load_ushort v234, v137, s[24:25]
	global_load_ushort v235, v137, s[24:25] offset:128
	v_add_u32_e32 v136, 0x1000, v136
	v_add_u32_e32 v137, 0x1000, v137
	s_cmp_eq_u32 s37, s5
	s_cselect_b32 s4, 0, -1
	ds_read_b128 v[192:195], v135 offset:64
	ds_read_b128 v[196:199], v135 offset:80
	ds_read_b128 v[200:203], v135 offset:96
	ds_read_b128 v[204:207], v135 offset:112
	ds_read_b128 v[208:211], v135 offset:320
	ds_read_b128 v[212:215], v135 offset:336
	ds_read_b128 v[216:219], v135 offset:352
	ds_read_b128 v[220:223], v135 offset:368
	s_waitcnt lgkmcnt(8)
	v_pk_fma_f32 v[0:1], v[148:149], v[0:1], v[250:251] op_sel_hi:[1,1,0]
	v_pk_fma_f32 v[2:3], v[150:151], v[2:3], v[250:251] op_sel_hi:[1,1,0]
	v_pk_fma_f32 v[4:5], v[152:153], v[4:5], v[250:251] op_sel_hi:[1,1,0]
	v_pk_fma_f32 v[6:7], v[154:155], v[6:7], v[250:251] op_sel_hi:[1,1,0]
	v_pk_fma_f32 v[240:241], v[0:1], v[164:165], 0 op_sel_hi:[1,1,0]
	v_pk_fma_f32 v[244:245], v[2:3], v[166:167], 0 op_sel_hi:[1,1,0]
	v_pk_fma_f32 v[240:241], v[4:5], v[168:169], v[240:241]
	v_pk_fma_f32 v[244:245], v[6:7], v[170:171], v[244:245]
	v_pk_fma_f32 v[8:9], v[156:157], v[8:9], v[250:251] op_sel_hi:[1,1,0]
	v_pk_fma_f32 v[10:11], v[158:159], v[10:11], v[250:251] op_sel_hi:[1,1,0]
	v_pk_fma_f32 v[12:13], v[160:161], v[12:13], v[250:251] op_sel_hi:[1,1,0]
	v_pk_fma_f32 v[14:15], v[162:163], v[14:15], v[250:251] op_sel_hi:[1,1,0]
	v_pk_fma_f32 v[240:241], v[8:9], v[172:173], v[240:241]
	v_pk_fma_f32 v[244:245], v[10:11], v[174:175], v[244:245]
	v_pk_fma_f32 v[240:241], v[12:13], v[176:177], v[240:241]
	v_pk_fma_f32 v[244:245], v[14:15], v[178:179], v[244:245]
	v_pk_fma_f32 v[64:65], v[148:149], v[64:65], v[250:251] op_sel:[0,0,1] op_sel_hi:[1,1,1]
	v_pk_fma_f32 v[66:67], v[150:151], v[66:67], v[250:251] op_sel:[0,0,1] op_sel_hi:[1,1,1]
	v_pk_fma_f32 v[68:69], v[152:153], v[68:69], v[250:251] op_sel:[0,0,1] op_sel_hi:[1,1,1]
	v_pk_fma_f32 v[70:71], v[154:155], v[70:71], v[250:251] op_sel:[0,0,1] op_sel_hi:[1,1,1]
	v_pk_fma_f32 v[246:247], v[64:65], v[164:165], 0 op_sel_hi:[1,1,0]
	v_pk_fma_f32 v[248:249], v[66:67], v[166:167], 0 op_sel_hi:[1,1,0]
	v_pk_fma_f32 v[246:247], v[68:69], v[168:169], v[246:247]
	v_pk_fma_f32 v[248:249], v[70:71], v[170:171], v[248:249]
	v_pk_fma_f32 v[72:73], v[156:157], v[72:73], v[250:251] op_sel:[0,0,1] op_sel_hi:[1,1,1]
	v_pk_fma_f32 v[74:75], v[158:159], v[74:75], v[250:251] op_sel:[0,0,1] op_sel_hi:[1,1,1]
	v_pk_fma_f32 v[76:77], v[160:161], v[76:77], v[250:251] op_sel:[0,0,1] op_sel_hi:[1,1,1]
	v_pk_fma_f32 v[78:79], v[162:163], v[78:79], v[250:251] op_sel:[0,0,1] op_sel_hi:[1,1,1]
	v_pk_fma_f32 v[246:247], v[72:73], v[172:173], v[246:247]
	v_pk_fma_f32 v[248:249], v[74:75], v[174:175], v[248:249]
	v_pk_fma_f32 v[246:247], v[76:77], v[176:177], v[246:247]
	v_pk_fma_f32 v[248:249], v[78:79], v[178:179], v[248:249]
	v_lshlrev_b32_e32 v140, 16, v237
	v_lshlrev_b32_e32 v141, 16, v236
	v_mul_f32_e32 v142, 0xbfb8aa3b, v140
	v_mul_f32_e32 v143, 0xbfb8aa3b, v141
	v_exp_f32_e32 v142, v142
	v_exp_f32_e32 v143, v143
	v_add_f32_e32 v142, 1.0, v142
	v_add_f32_e32 v143, 1.0, v143
	v_rcp_f32_e32 v142, v142
	v_rcp_f32_e32 v143, v143
	v_fma_f32 v142, v131, v142, v130
	v_mul_f32_e32 v143, v143, v141
	v_mul_f32_e32 v132, v132, v142
	ds_write2st64_b32 v134, v142, v143 offset0:2 offset1:3
	v_mov_b32_e32 v182, v143
	s_waitcnt vmcnt(12)
; __device__ __forceinline__ float bf2f(unsigned short b) { return __uint_as_float((unsigned)b << 16); }
; __device__ __forceinline__ unsigned short f2bf(float f) { unsigned u = __float_as_uint(f); u += 0x7FFFu + ((u >> 16) & 1u); return (unsigned short)(u >> 16); }
; __device__ __forceinline__ float sigm(float x) { return __builtin_amdgcn_rcpf(1.0f + __expf(-x)); }
; __device__ __forceinline__ f2 pfma(f2 a, f2 b, f2 c) { return __builtin_elementwise_fma(a, b, c); }
; __device__ __forceinline__ void hgrn_scan(const bf16_t* __restrict__ PH, int t0, int nsteps, int h, int half, int kh, int lane, float lb, f2 (&S)[32], float& cp, bf16_t* __restrict__ OHp, float* __restrict__ ckp, LAS float* L) {
;     ...
;         const float ql = bf2f(q1[0]), fz = bf2f(q1[1]), v = bf2f(q1[2]);
; #pragma unroll
;         for (int j = 0; j < 3; ++j) { q1[j] = q2[j]; q2[j] = q3[j]; }
;         { const bf16_t* r = row + (size_t)(s + 3 < nsteps ? s + 3 : nsteps - 1) * 2048; q3[0] = r[0]; q3[1] = r[512]; q3[2] = r[voff]; }
;         const float fl = lb + (1.0f - lb) * sigm(fz);
;         cp *= fl;
;         if (ckp && (s & 31) == 31 && s < 127) ckp[(s >> 5) * 128 + lane] = cp;
;         L[lane] = fl; L[64 + lane] = ql * sigm(ql);
;         f32x4 F[2][4], Q[2][4];
; #pragma unroll
;         for (int i = 0; i < 4; ++i) { F[0][i] = pf[i]; Q[0][i] = pf[16 + i]; }
;         const f2 v2 = {v, v}; f2 o2 = {0.f, 0.f}, o3 = {0.f, 0.f};
; #pragma unroll
;         for (int g = 0; g < 4; ++g) {
;             if (g < 3) {
; #pragma unroll
;                 for (int i = 0; i < 4; ++i) { F[(g + 1) & 1][i] = pf[(g + 1) * 4 + i]; Q[(g + 1) & 1][i] = pf[16 + (g + 1) * 4 + i]; } }
;             __builtin_amdgcn_sched_barrier(0);
; #pragma unroll
;             for (int i = 0; i < 4; ++i) {
;                 const f32x4 f4 = F[g & 1][i], q4 = Q[g & 1][i]; const int idx = (g * 4 + i) * 2;
;                 const f2 f01 = {f4[0], f4[1]}, f23 = {f4[2], f4[3]}, q01 = {q4[0], q4[1]}, q23 = {q4[2], q4[3]};
;                 S[idx] = pfma(f01, S[idx] - v2, v2); o2 = pfma(S[idx], q01, o2);
;                 S[idx + 1] = pfma(f23, S[idx + 1] - v2, v2); o3 = pfma(S[idx + 1], q23, o3);
;             }
;         }
;         OHp[(size_t)(t0 + s) * 512 + h * 128 + half * 64 + lane] = f2bf((o2[0] + o2[1]) + (o3[0] + o3[1]));
	v_lshlrev_b32_e32 v180, 16, v226
	v_lshlrev_b32_e32 v181, 16, v227
	v_and_b32_e32 v180, s4, v180
	v_and_b32_e32 v181, s4, v181
	v_pk_add_f32 v[252:253], v[254:255], v[180:181] neg_lo:[0,1] neg_hi:[0,1]
	ds_read_b128 v[148:151], v135 offset:128
	ds_read_b128 v[152:155], v135 offset:144
	ds_read_b128 v[156:159], v135 offset:160
	ds_read_b128 v[160:163], v135 offset:176
	ds_read_b128 v[164:167], v135 offset:384
	ds_read_b128 v[168:171], v135 offset:400
	ds_read_b128 v[172:175], v135 offset:416
	ds_read_b128 v[176:179], v135 offset:432
	v_add_f32_dpp v182, v182, v182 quad_perm:[1,0,3,2] row_mask:0xf bank_mask:0xf bound_ctrl:1
	s_waitcnt lgkmcnt(9)
	v_pk_fma_f32 v[16:17], v[192:193], v[16:17], v[250:251] op_sel_hi:[1,1,0]
	v_pk_fma_f32 v[18:19], v[194:195], v[18:19], v[250:251] op_sel_hi:[1,1,0]
	v_pk_fma_f32 v[20:21], v[196:197], v[20:21], v[250:251] op_sel_hi:[1,1,0]
	v_pk_fma_f32 v[22:23], v[198:199], v[22:23], v[250:251] op_sel_hi:[1,1,0]
	v_pk_fma_f32 v[240:241], v[16:17], v[208:209], v[240:241]
	v_pk_fma_f32 v[244:245], v[18:19], v[210:211], v[244:245]
	v_pk_fma_f32 v[240:241], v[20:21], v[212:213], v[240:241]
	v_pk_fma_f32 v[244:245], v[22:23], v[214:215], v[244:245]
	v_pk_fma_f32 v[24:25], v[200:201], v[24:25], v[250:251] op_sel_hi:[1,1,0]
	v_pk_fma_f32 v[26:27], v[202:203], v[26:27], v[250:251] op_sel_hi:[1,1,0]
	v_pk_fma_f32 v[28:29], v[204:205], v[28:29], v[250:251] op_sel_hi:[1,1,0]
	v_pk_fma_f32 v[30:31], v[206:207], v[30:31], v[250:251] op_sel_hi:[1,1,0]
	v_pk_fma_f32 v[240:241], v[24:25], v[216:217], v[240:241]
	v_pk_fma_f32 v[244:245], v[26:27], v[218:219], v[244:245]
	v_pk_fma_f32 v[240:241], v[28:29], v[220:221], v[240:241]
	v_pk_fma_f32 v[244:245], v[30:31], v[222:223], v[244:245]
	v_pk_fma_f32 v[80:81], v[192:193], v[80:81], v[250:251] op_sel:[0,0,1] op_sel_hi:[1,1,1]
	v_pk_fma_f32 v[82:83], v[194:195], v[82:83], v[250:251] op_sel:[0,0,1] op_sel_hi:[1,1,1]
	v_pk_fma_f32 v[84:85], v[196:197], v[84:85], v[250:251] op_sel:[0,0,1] op_sel_hi:[1,1,1]
	v_pk_fma_f32 v[86:87], v[198:199], v[86:87], v[250:251] op_sel:[0,0,1] op_sel_hi:[1,1,1]
	v_pk_fma_f32 v[246:247], v[80:81], v[208:209], v[246:247]
	v_pk_fma_f32 v[248:249], v[82:83], v[210:211], v[248:249]
	v_pk_fma_f32 v[246:247], v[84:85], v[212:213], v[246:247]
	v_pk_fma_f32 v[248:249], v[86:87], v[214:215], v[248:249]
	v_pk_fma_f32 v[88:89], v[200:201], v[88:89], v[250:251] op_sel:[0,0,1] op_sel_hi:[1,1,1]
	v_pk_fma_f32 v[90:91], v[202:203], v[90:91], v[250:251] op_sel:[0,0,1] op_sel_hi:[1,1,1]
	v_pk_fma_f32 v[92:93], v[204:205], v[92:93], v[250:251] op_sel:[0,0,1] op_sel_hi:[1,1,1]
	v_pk_fma_f32 v[94:95], v[206:207], v[94:95], v[250:251] op_sel:[0,0,1] op_sel_hi:[1,1,1]
	v_pk_fma_f32 v[246:247], v[88:89], v[216:217], v[246:247]
	v_pk_fma_f32 v[248:249], v[90:91], v[218:219], v[248:249]
	v_pk_fma_f32 v[246:247], v[92:93], v[220:221], v[246:247]
	v_pk_fma_f32 v[248:249], v[94:95], v[222:223], v[248:249]
	v_add_f32_dpp v182, v182, v182 quad_perm:[2,3,0,1] row_mask:0xf bank_mask:0xf bound_ctrl:1
	ds_read_b128 v[192:195], v135 offset:192
	ds_read_b128 v[196:199], v135 offset:208
	ds_read_b128 v[200:203], v135 offset:224
	ds_read_b128 v[204:207], v135 offset:240
	ds_read_b128 v[208:211], v135 offset:448
	ds_read_b128 v[212:215], v135 offset:464
	ds_read_b128 v[216:219], v135 offset:480
	ds_read_b128 v[220:223], v135 offset:496
	v_add_f32_dpp v182, v182, v182 row_half_mirror row_mask:0xf bank_mask:0xf bound_ctrl:1
	s_waitcnt lgkmcnt(8)
	v_pk_fma_f32 v[32:33], v[148:149], v[32:33], v[250:251] op_sel_hi:[1,1,0]
	v_pk_fma_f32 v[34:35], v[150:151], v[34:35], v[250:251] op_sel_hi:[1,1,0]
	v_pk_fma_f32 v[36:37], v[152:153], v[36:37], v[250:251] op_sel_hi:[1,1,0]
	v_pk_fma_f32 v[38:39], v[154:155], v[38:39], v[250:251] op_sel_hi:[1,1,0]
	v_pk_fma_f32 v[240:241], v[32:33], v[164:165], v[240:241]
	v_pk_fma_f32 v[244:245], v[34:35], v[166:167], v[244:245]
	v_pk_fma_f32 v[240:241], v[36:37], v[168:169], v[240:241]
	v_pk_fma_f32 v[244:245], v[38:39], v[170:171], v[244:245]
	v_pk_fma_f32 v[40:41], v[156:157], v[40:41], v[250:251] op_sel_hi:[1,1,0]
	v_pk_fma_f32 v[42:43], v[158:159], v[42:43], v[250:251] op_sel_hi:[1,1,0]
	v_pk_fma_f32 v[44:45], v[160:161], v[44:45], v[250:251] op_sel_hi:[1,1,0]
	v_pk_fma_f32 v[46:47], v[162:163], v[46:47], v[250:251] op_sel_hi:[1,1,0]
	v_pk_fma_f32 v[240:241], v[40:41], v[172:173], v[240:241]
	v_pk_fma_f32 v[244:245], v[42:43], v[174:175], v[244:245]
	v_pk_fma_f32 v[240:241], v[44:45], v[176:177], v[240:241]
	v_pk_fma_f32 v[244:245], v[46:47], v[178:179], v[244:245]
	v_pk_fma_f32 v[96:97], v[148:149], v[96:97], v[250:251] op_sel:[0,0,1] op_sel_hi:[1,1,1]
	v_pk_fma_f32 v[98:99], v[150:151], v[98:99], v[250:251] op_sel:[0,0,1] op_sel_hi:[1,1,1]
	v_pk_fma_f32 v[100:101], v[152:153], v[100:101], v[250:251] op_sel:[0,0,1] op_sel_hi:[1,1,1]
	v_pk_fma_f32 v[102:103], v[154:155], v[102:103], v[250:251] op_sel:[0,0,1] op_sel_hi:[1,1,1]
	v_pk_fma_f32 v[246:247], v[96:97], v[164:165], v[246:247]
	v_pk_fma_f32 v[248:249], v[98:99], v[166:167], v[248:249]
	v_pk_fma_f32 v[246:247], v[100:101], v[168:169], v[246:247]
	v_pk_fma_f32 v[248:249], v[102:103], v[170:171], v[248:249]
	v_pk_fma_f32 v[104:105], v[156:157], v[104:105], v[250:251] op_sel:[0,0,1] op_sel_hi:[1,1,1]
	v_pk_fma_f32 v[106:107], v[158:159], v[106:107], v[250:251] op_sel:[0,0,1] op_sel_hi:[1,1,1]
	v_pk_fma_f32 v[108:109], v[160:161], v[108:109], v[250:251] op_sel:[0,0,1] op_sel_hi:[1,1,1]
	v_pk_fma_f32 v[110:111], v[162:163], v[110:111], v[250:251] op_sel:[0,0,1] op_sel_hi:[1,1,1]
	v_pk_fma_f32 v[246:247], v[104:105], v[172:173], v[246:247]
	v_pk_fma_f32 v[248:249], v[106:107], v[174:175], v[248:249]
	v_pk_fma_f32 v[246:247], v[108:109], v[176:177], v[246:247]
	v_pk_fma_f32 v[248:249], v[110:111], v[178:179], v[248:249]
	v_add_f32_dpp v182, v182, v182 row_mirror row_mask:0xf bank_mask:0xf bound_ctrl:1
	ds_read_b128 v[148:151], v135 offset:512
	ds_read_b128 v[152:155], v135 offset:528
	ds_read_b128 v[156:159], v135 offset:544
	ds_read_b128 v[160:163], v135 offset:560
	ds_read_b128 v[164:167], v135 offset:768
	ds_read_b128 v[168:171], v135 offset:784
	ds_read_b128 v[172:175], v135 offset:800
	ds_read_b128 v[176:179], v135 offset:816
	v_readlane_b32 s0, v182, 0
	v_readlane_b32 s1, v182, 16
	v_readlane_b32 s6, v182, 32
	v_readlane_b32 s7, v182, 48
	s_waitcnt lgkmcnt(8)
; __device__ __forceinline__ float bf2f(unsigned short b) { return __uint_as_float((unsigned)b << 16); }
; __device__ __forceinline__ unsigned short f2bf(float f) { unsigned u = __float_as_uint(f); u += 0x7FFFu + ((u >> 16) & 1u); return (unsigned short)(u >> 16); }
; __device__ __forceinline__ float sigm(float x) { return __builtin_amdgcn_rcpf(1.0f + __expf(-x)); }
; __device__ __forceinline__ f2 pfma(f2 a, f2 b, f2 c) { return __builtin_elementwise_fma(a, b, c); }
; __device__ __forceinline__ void hgrn_scan(const bf16_t* __restrict__ PH, int t0, int nsteps, int h, int half, int kh, int lane, float lb, f2 (&S)[32], float& cp, bf16_t* __restrict__ OHp, float* __restrict__ ckp, LAS float* L) {
;     ...
;         const float ql = bf2f(q1[0]), fz = bf2f(q1[1]), v = bf2f(q1[2]);
; #pragma unroll
;         for (int j = 0; j < 3; ++j) { q1[j] = q2[j]; q2[j] = q3[j]; }
;         { const bf16_t* r = row + (size_t)(s + 3 < nsteps ? s + 3 : nsteps - 1) * 2048; q3[0] = r[0]; q3[1] = r[512]; q3[2] = r[voff]; }
;         const float fl = lb + (1.0f - lb) * sigm(fz);
;         cp *= fl;
;         if (ckp && (s & 31) == 31 && s < 127) ckp[(s >> 5) * 128 + lane] = cp;
;         L[lane] = fl; L[64 + lane] = ql * sigm(ql);
;         f32x4 F[2][4], Q[2][4];
; #pragma unroll
;         for (int i = 0; i < 4; ++i) { F[0][i] = pf[i]; Q[0][i] = pf[16 + i]; }
;         const f2 v2 = {v, v}; f2 o2 = {0.f, 0.f}, o3 = {0.f, 0.f};
; #pragma unroll
;         for (int g = 0; g < 4; ++g) {
;             if (g < 3) {
; #pragma unroll
;                 for (int i = 0; i < 4; ++i) { F[(g + 1) & 1][i] = pf[(g + 1) * 4 + i]; Q[(g + 1) & 1][i] = pf[16 + (g + 1) * 4 + i]; } }
;             __builtin_amdgcn_sched_barrier(0);
; #pragma unroll
;             for (int i = 0; i < 4; ++i) {
;                 const f32x4 f4 = F[g & 1][i], q4 = Q[g & 1][i]; const int idx = (g * 4 + i) * 2;
;                 const f2 f01 = {f4[0], f4[1]}, f23 = {f4[2], f4[3]}, q01 = {q4[0], q4[1]}, q23 = {q4[2], q4[3]};
;                 S[idx] = pfma(f01, S[idx] - v2, v2); o2 = pfma(S[idx], q01, o2);
;                 S[idx + 1] = pfma(f23, S[idx + 1] - v2, v2); o3 = pfma(S[idx + 1], q23, o3);
;             }
;         }
;         OHp[(size_t)(t0 + s) * 512 + h * 128 + half * 64 + lane] = f2bf((o2[0] + o2[1]) + (o3[0] + o3[1]));
	v_pk_fma_f32 v[48:49], v[192:193], v[48:49], v[250:251] op_sel_hi:[1,1,0]
	v_pk_fma_f32 v[50:51], v[194:195], v[50:51], v[250:251] op_sel_hi:[1,1,0]
	v_pk_fma_f32 v[52:53], v[196:197], v[52:53], v[250:251] op_sel_hi:[1,1,0]
	v_pk_fma_f32 v[54:55], v[198:199], v[54:55], v[250:251] op_sel_hi:[1,1,0]
	v_pk_fma_f32 v[240:241], v[48:49], v[208:209], v[240:241]
	v_pk_fma_f32 v[244:245], v[50:51], v[210:211], v[244:245]
	v_pk_fma_f32 v[240:241], v[52:53], v[212:213], v[240:241]
	v_pk_fma_f32 v[244:245], v[54:55], v[214:215], v[244:245]
	v_pk_fma_f32 v[56:57], v[200:201], v[56:57], v[250:251] op_sel_hi:[1,1,0]
	v_pk_fma_f32 v[58:59], v[202:203], v[58:59], v[250:251] op_sel_hi:[1,1,0]
	v_pk_fma_f32 v[60:61], v[204:205], v[60:61], v[250:251] op_sel_hi:[1,1,0]
	v_pk_fma_f32 v[62:63], v[206:207], v[62:63], v[250:251] op_sel_hi:[1,1,0]
	v_pk_fma_f32 v[240:241], v[56:57], v[216:217], v[240:241]
	v_pk_fma_f32 v[244:245], v[58:59], v[218:219], v[244:245]
	v_pk_fma_f32 v[240:241], v[60:61], v[220:221], v[240:241]
	v_pk_fma_f32 v[244:245], v[62:63], v[222:223], v[244:245]
	v_pk_fma_f32 v[112:113], v[192:193], v[112:113], v[250:251] op_sel:[0,0,1] op_sel_hi:[1,1,1]
	v_pk_fma_f32 v[114:115], v[194:195], v[114:115], v[250:251] op_sel:[0,0,1] op_sel_hi:[1,1,1]
	v_pk_fma_f32 v[116:117], v[196:197], v[116:117], v[250:251] op_sel:[0,0,1] op_sel_hi:[1,1,1]
	v_pk_fma_f32 v[118:119], v[198:199], v[118:119], v[250:251] op_sel:[0,0,1] op_sel_hi:[1,1,1]
	v_pk_fma_f32 v[246:247], v[112:113], v[208:209], v[246:247]
	v_pk_fma_f32 v[248:249], v[114:115], v[210:211], v[248:249]
	v_pk_fma_f32 v[246:247], v[116:117], v[212:213], v[246:247]
	v_pk_fma_f32 v[248:249], v[118:119], v[214:215], v[248:249]
	v_pk_fma_f32 v[120:121], v[200:201], v[120:121], v[250:251] op_sel:[0,0,1] op_sel_hi:[1,1,1]
	v_pk_fma_f32 v[122:123], v[202:203], v[122:123], v[250:251] op_sel:[0,0,1] op_sel_hi:[1,1,1]
	v_pk_fma_f32 v[124:125], v[204:205], v[124:125], v[250:251] op_sel:[0,0,1] op_sel_hi:[1,1,1]
	v_pk_fma_f32 v[126:127], v[206:207], v[126:127], v[250:251] op_sel:[0,0,1] op_sel_hi:[1,1,1]
	v_pk_fma_f32 v[246:247], v[120:121], v[216:217], v[246:247]
	v_pk_fma_f32 v[248:249], v[122:123], v[218:219], v[248:249]
	v_pk_fma_f32 v[246:247], v[124:125], v[220:221], v[246:247]
	v_pk_fma_f32 v[248:249], v[126:127], v[222:223], v[248:249]
	v_mov_b32_e32 v183, s0
	v_add_f32_e32 v183, s1, v183
	v_add_f32_e32 v183, s6, v183
	v_add_f32_e32 v183, s7, v183
	v_add_f32_e32 v240, v240, v241
	v_add_f32_e32 v244, v244, v245
	v_add_f32_e32 v240, v240, v244
	v_fmac_f32_e32 v240, s2, v254
	v_bfe_u32 v244, v240, 16, 1
	v_add3_u32 v240, v240, v244, s69
	global_store_short_d16_hi v138, v240, s[26:27]
	v_add_f32_e32 v246, v246, v247
	v_add_f32_e32 v248, v248, v249
	v_add_f32_e32 v246, v246, v248
	v_fmac_f32_e32 v246, s2, v255
	v_bfe_u32 v248, v246, 16, 1
	v_add3_u32 v246, v246, v248, s69
	global_store_short_d16_hi v138, v246, s[26:27] offset:128
	v_readfirstlane_b32 s2, v183
	v_mov_b64_e32 v[250:251], v[252:253]
	v_mov_b64_e32 v[254:255], v[180:181]
	v_add_u32_e32 v138, 0x400, v138
	global_load_ushort v236, v136, s[24:25]
	global_load_ushort v237, v136, s[24:25] offset:1024
	global_load_ushort v238, v137, s[24:25]
	global_load_ushort v239, v137, s[24:25] offset:128
	v_add_u32_e32 v136, 0x1000, v136
	v_add_u32_e32 v137, 0x1000, v137
	v_mov_b32_e32 v133, v132
	s_cmp_lg_u32 s36, 32
	s_cbranch_scc1 .Lhs_m_nock
	s_and_b32 s0, s37, 7
	s_cmp_lg_u32 s0, 7
	s_cbranch_scc1 .Lhs_m_nock
	s_cmp_eq_u32 s37, 31
	s_cbranch_scc1 .Lhs_m_nock
	s_lshr_b32 s0, s37, 3
	s_lshl_b32 s0, s0, 9
	s_add_u32 s0, s42, s0
	s_addc_u32 s1, s43, 0
	global_store_dword v147, v133, s[0:1]
.Lhs_m_nock:
	s_cmp_eq_u32 s37, s5
	s_cselect_b32 s4, 0, -1
	ds_read_b128 v[192:195], v135 offset:576
	ds_read_b128 v[196:199], v135 offset:592
	ds_read_b128 v[200:203], v135 offset:608
	ds_read_b128 v[204:207], v135 offset:624
	ds_read_b128 v[208:211], v135 offset:832
	ds_read_b128 v[212:215], v135 offset:848
	ds_read_b128 v[216:219], v135 offset:864
	ds_read_b128 v[220:223], v135 offset:880
	s_waitcnt lgkmcnt(8)
	v_pk_fma_f32 v[0:1], v[148:149], v[0:1], v[250:251] op_sel_hi:[1,1,0]
	v_pk_fma_f32 v[2:3], v[150:151], v[2:3], v[250:251] op_sel_hi:[1,1,0]
	v_pk_fma_f32 v[4:5], v[152:153], v[4:5], v[250:251] op_sel_hi:[1,1,0]
	v_pk_fma_f32 v[6:7], v[154:155], v[6:7], v[250:251] op_sel_hi:[1,1,0]
	v_pk_fma_f32 v[240:241], v[0:1], v[164:165], 0 op_sel_hi:[1,1,0]
	v_pk_fma_f32 v[244:245], v[2:3], v[166:167], 0 op_sel_hi:[1,1,0]
	v_pk_fma_f32 v[240:241], v[4:5], v[168:169], v[240:241]
	v_pk_fma_f32 v[244:245], v[6:7], v[170:171], v[244:245]
	v_pk_fma_f32 v[8:9], v[156:157], v[8:9], v[250:251] op_sel_hi:[1,1,0]
	v_pk_fma_f32 v[10:11], v[158:159], v[10:11], v[250:251] op_sel_hi:[1,1,0]
	v_pk_fma_f32 v[12:13], v[160:161], v[12:13], v[250:251] op_sel_hi:[1,1,0]
	v_pk_fma_f32 v[14:15], v[162:163], v[14:15], v[250:251] op_sel_hi:[1,1,0]
	v_pk_fma_f32 v[240:241], v[8:9], v[172:173], v[240:241]
	v_pk_fma_f32 v[244:245], v[10:11], v[174:175], v[244:245]
	v_pk_fma_f32 v[240:241], v[12:13], v[176:177], v[240:241]
	v_pk_fma_f32 v[244:245], v[14:15], v[178:179], v[244:245]
	v_pk_fma_f32 v[64:65], v[148:149], v[64:65], v[250:251] op_sel:[0,0,1] op_sel_hi:[1,1,1]
	v_pk_fma_f32 v[66:67], v[150:151], v[66:67], v[250:251] op_sel:[0,0,1] op_sel_hi:[1,1,1]
	v_pk_fma_f32 v[68:69], v[152:153], v[68:69], v[250:251] op_sel:[0,0,1] op_sel_hi:[1,1,1]
	v_pk_fma_f32 v[70:71], v[154:155], v[70:71], v[250:251] op_sel:[0,0,1] op_sel_hi:[1,1,1]
	v_pk_fma_f32 v[246:247], v[64:65], v[164:165], 0 op_sel_hi:[1,1,0]
	v_pk_fma_f32 v[248:249], v[66:67], v[166:167], 0 op_sel_hi:[1,1,0]
	v_pk_fma_f32 v[246:247], v[68:69], v[168:169], v[246:247]
	v_pk_fma_f32 v[248:249], v[70:71], v[170:171], v[248:249]
	v_pk_fma_f32 v[72:73], v[156:157], v[72:73], v[250:251] op_sel:[0,0,1] op_sel_hi:[1,1,1]
	v_pk_fma_f32 v[74:75], v[158:159], v[74:75], v[250:251] op_sel:[0,0,1] op_sel_hi:[1,1,1]
	v_pk_fma_f32 v[76:77], v[160:161], v[76:77], v[250:251] op_sel:[0,0,1] op_sel_hi:[1,1,1]
	v_pk_fma_f32 v[78:79], v[162:163], v[78:79], v[250:251] op_sel:[0,0,1] op_sel_hi:[1,1,1]
	v_pk_fma_f32 v[246:247], v[72:73], v[172:173], v[246:247]
	v_pk_fma_f32 v[248:249], v[74:75], v[174:175], v[248:249]
	v_pk_fma_f32 v[246:247], v[76:77], v[176:177], v[246:247]
	v_pk_fma_f32 v[248:249], v[78:79], v[178:179], v[248:249]
	v_lshlrev_b32_e32 v140, 16, v225
	v_lshlrev_b32_e32 v141, 16, v224
	v_mul_f32_e32 v142, 0xbfb8aa3b, v140
	v_mul_f32_e32 v143, 0xbfb8aa3b, v141
	v_exp_f32_e32 v142, v142
	v_exp_f32_e32 v143, v143
	v_add_f32_e32 v142, 1.0, v142
	v_add_f32_e32 v143, 1.0, v143
	v_rcp_f32_e32 v142, v142
	v_rcp_f32_e32 v143, v143
	v_fma_f32 v142, v131, v142, v130
	v_mul_f32_e32 v143, v143, v141
	v_mul_f32_e32 v132, v132, v142
	ds_write2st64_b32 v134, v142, v143 offset0:0 offset1:1
	v_mov_b32_e32 v182, v143
	s_waitcnt vmcnt(12)
; __device__ __forceinline__ float bf2f(unsigned short b) { return __uint_as_float((unsigned)b << 16); }
; __device__ __forceinline__ unsigned short f2bf(float f) { unsigned u = __float_as_uint(f); u += 0x7FFFu + ((u >> 16) & 1u); return (unsigned short)(u >> 16); }
; __device__ __forceinline__ float sigm(float x) { return __builtin_amdgcn_rcpf(1.0f + __expf(-x)); }
; __device__ __forceinline__ f2 pfma(f2 a, f2 b, f2 c) { return __builtin_elementwise_fma(a, b, c); }
; __device__ __forceinline__ void hgrn_scan(const bf16_t* __restrict__ PH, int t0, int nsteps, int h, int half, int kh, int lane, float lb, f2 (&S)[32], float& cp, bf16_t* __restrict__ OHp, float* __restrict__ ckp, LAS float* L) {
;     ...
;         const float ql = bf2f(q1[0]), fz = bf2f(q1[1]), v = bf2f(q1[2]);
; #pragma unroll
;         for (int j = 0; j < 3; ++j) { q1[j] = q2[j]; q2[j] = q3[j]; }
;         { const bf16_t* r = row + (size_t)(s + 3 < nsteps ? s + 3 : nsteps - 1) * 2048; q3[0] = r[0]; q3[1] = r[512]; q3[2] = r[voff]; }
;         const float fl = lb + (1.0f - lb) * sigm(fz);
;         cp *= fl;
;         if (ckp && (s & 31) == 31 && s < 127) ckp[(s >> 5) * 128 + lane] = cp;
;         L[lane] = fl; L[64 + lane] = ql * sigm(ql);
;         f32x4 F[2][4], Q[2][4];
; #pragma unroll
;         for (int i = 0; i < 4; ++i) { F[0][i] = pf[i]; Q[0][i] = pf[16 + i]; }
;         const f2 v2 = {v, v}; f2 o2 = {0.f, 0.f}, o3 = {0.f, 0.f};
; #pragma unroll
;         for (int g = 0; g < 4; ++g) {
;             if (g < 3) {
; #pragma unroll
;                 for (int i = 0; i < 4; ++i) { F[(g + 1) & 1][i] = pf[(g + 1) * 4 + i]; Q[(g + 1) & 1][i] = pf[16 + (g + 1) * 4 + i]; } }
;             __builtin_amdgcn_sched_barrier(0);
; #pragma unroll
;             for (int i = 0; i < 4; ++i) {
;                 const f32x4 f4 = F[g & 1][i], q4 = Q[g & 1][i]; const int idx = (g * 4 + i) * 2;
;                 const f2 f01 = {f4[0], f4[1]}, f23 = {f4[2], f4[3]}, q01 = {q4[0], q4[1]}, q23 = {q4[2], q4[3]};
;                 S[idx] = pfma(f01, S[idx] - v2, v2); o2 = pfma(S[idx], q01, o2);
;                 S[idx + 1] = pfma(f23, S[idx + 1] - v2, v2); o3 = pfma(S[idx + 1], q23, o3);
;             }
;         }
;         OHp[(size_t)(t0 + s) * 512 + h * 128 + half * 64 + lane] = f2bf((o2[0] + o2[1]) + (o3[0] + o3[1]));
	v_lshlrev_b32_e32 v180, 16, v230
	v_lshlrev_b32_e32 v181, 16, v231
	v_and_b32_e32 v180, s4, v180
	v_and_b32_e32 v181, s4, v181
	v_pk_add_f32 v[252:253], v[254:255], v[180:181] neg_lo:[0,1] neg_hi:[0,1]
	ds_read_b128 v[148:151], v135 offset:640
	ds_read_b128 v[152:155], v135 offset:656
	ds_read_b128 v[156:159], v135 offset:672
	ds_read_b128 v[160:163], v135 offset:688
	ds_read_b128 v[164:167], v135 offset:896
	ds_read_b128 v[168:171], v135 offset:912
	ds_read_b128 v[172:175], v135 offset:928
	ds_read_b128 v[176:179], v135 offset:944
	v_add_f32_dpp v182, v182, v182 quad_perm:[1,0,3,2] row_mask:0xf bank_mask:0xf bound_ctrl:1
	s_waitcnt lgkmcnt(9)
	v_pk_fma_f32 v[16:17], v[192:193], v[16:17], v[250:251] op_sel_hi:[1,1,0]
	v_pk_fma_f32 v[18:19], v[194:195], v[18:19], v[250:251] op_sel_hi:[1,1,0]
	v_pk_fma_f32 v[20:21], v[196:197], v[20:21], v[250:251] op_sel_hi:[1,1,0]
	v_pk_fma_f32 v[22:23], v[198:199], v[22:23], v[250:251] op_sel_hi:[1,1,0]
	v_pk_fma_f32 v[240:241], v[16:17], v[208:209], v[240:241]
	v_pk_fma_f32 v[244:245], v[18:19], v[210:211], v[244:245]
	v_pk_fma_f32 v[240:241], v[20:21], v[212:213], v[240:241]
	v_pk_fma_f32 v[244:245], v[22:23], v[214:215], v[244:245]
	v_pk_fma_f32 v[24:25], v[200:201], v[24:25], v[250:251] op_sel_hi:[1,1,0]
	v_pk_fma_f32 v[26:27], v[202:203], v[26:27], v[250:251] op_sel_hi:[1,1,0]
	v_pk_fma_f32 v[28:29], v[204:205], v[28:29], v[250:251] op_sel_hi:[1,1,0]
	v_pk_fma_f32 v[30:31], v[206:207], v[30:31], v[250:251] op_sel_hi:[1,1,0]
	v_pk_fma_f32 v[240:241], v[24:25], v[216:217], v[240:241]
	v_pk_fma_f32 v[244:245], v[26:27], v[218:219], v[244:245]
	v_pk_fma_f32 v[240:241], v[28:29], v[220:221], v[240:241]
	v_pk_fma_f32 v[244:245], v[30:31], v[222:223], v[244:245]
	v_pk_fma_f32 v[80:81], v[192:193], v[80:81], v[250:251] op_sel:[0,0,1] op_sel_hi:[1,1,1]
	v_pk_fma_f32 v[82:83], v[194:195], v[82:83], v[250:251] op_sel:[0,0,1] op_sel_hi:[1,1,1]
	v_pk_fma_f32 v[84:85], v[196:197], v[84:85], v[250:251] op_sel:[0,0,1] op_sel_hi:[1,1,1]
	v_pk_fma_f32 v[86:87], v[198:199], v[86:87], v[250:251] op_sel:[0,0,1] op_sel_hi:[1,1,1]
	v_pk_fma_f32 v[246:247], v[80:81], v[208:209], v[246:247]
	v_pk_fma_f32 v[248:249], v[82:83], v[210:211], v[248:249]
	v_pk_fma_f32 v[246:247], v[84:85], v[212:213], v[246:247]
	v_pk_fma_f32 v[248:249], v[86:87], v[214:215], v[248:249]
	v_pk_fma_f32 v[88:89], v[200:201], v[88:89], v[250:251] op_sel:[0,0,1] op_sel_hi:[1,1,1]
	v_pk_fma_f32 v[90:91], v[202:203], v[90:91], v[250:251] op_sel:[0,0,1] op_sel_hi:[1,1,1]
	v_pk_fma_f32 v[92:93], v[204:205], v[92:93], v[250:251] op_sel:[0,0,1] op_sel_hi:[1,1,1]
	v_pk_fma_f32 v[94:95], v[206:207], v[94:95], v[250:251] op_sel:[0,0,1] op_sel_hi:[1,1,1]
	v_pk_fma_f32 v[246:247], v[88:89], v[216:217], v[246:247]
	v_pk_fma_f32 v[248:249], v[90:91], v[218:219], v[248:249]
	v_pk_fma_f32 v[246:247], v[92:93], v[220:221], v[246:247]
	v_pk_fma_f32 v[248:249], v[94:95], v[222:223], v[248:249]
	v_add_f32_dpp v182, v182, v182 quad_perm:[2,3,0,1] row_mask:0xf bank_mask:0xf bound_ctrl:1
	ds_read_b128 v[192:195], v135 offset:704
	ds_read_b128 v[196:199], v135 offset:720
	ds_read_b128 v[200:203], v135 offset:736
	ds_read_b128 v[204:207], v135 offset:752
	ds_read_b128 v[208:211], v135 offset:960
	ds_read_b128 v[212:215], v135 offset:976
	ds_read_b128 v[216:219], v135 offset:992
	ds_read_b128 v[220:223], v135 offset:1008
	v_add_f32_dpp v182, v182, v182 row_half_mirror row_mask:0xf bank_mask:0xf bound_ctrl:1
	s_waitcnt lgkmcnt(8)
; __device__ __forceinline__ float bf2f(unsigned short b) { return __uint_as_float((unsigned)b << 16); }
; __device__ __forceinline__ unsigned short f2bf(float f) { unsigned u = __float_as_uint(f); u += 0x7FFFu + ((u >> 16) & 1u); return (unsigned short)(u >> 16); }
; __device__ __forceinline__ float sigm(float x) { return __builtin_amdgcn_rcpf(1.0f + __expf(-x)); }
; __device__ __forceinline__ f2 pfma(f2 a, f2 b, f2 c) { return __builtin_elementwise_fma(a, b, c); }
; __device__ __forceinline__ void hgrn_scan(const bf16_t* __restrict__ PH, int t0, int nsteps, int h, int half, int kh, int lane, float lb, f2 (&S)[32], float& cp, bf16_t* __restrict__ OHp, float* __restrict__ ckp, LAS float* L) {
;     ...
;         const float ql = bf2f(q1[0]), fz = bf2f(q1[1]), v = bf2f(q1[2]);
; #pragma unroll
;         for (int j = 0; j < 3; ++j) { q1[j] = q2[j]; q2[j] = q3[j]; }
;         { const bf16_t* r = row + (size_t)(s + 3 < nsteps ? s + 3 : nsteps - 1) * 2048; q3[0] = r[0]; q3[1] = r[512]; q3[2] = r[voff]; }
;         const float fl = lb + (1.0f - lb) * sigm(fz);
;         cp *= fl;
;         if (ckp && (s & 31) == 31 && s < 127) ckp[(s >> 5) * 128 + lane] = cp;
;         L[lane] = fl; L[64 + lane] = ql * sigm(ql);
;         f32x4 F[2][4], Q[2][4];
; #pragma unroll
;         for (int i = 0; i < 4; ++i) { F[0][i] = pf[i]; Q[0][i] = pf[16 + i]; }
;         const f2 v2 = {v, v}; f2 o2 = {0.f, 0.f}, o3 = {0.f, 0.f};
; #pragma unroll
;         for (int g = 0; g < 4; ++g) {
;             if (g < 3) {
; #pragma unroll
;                 for (int i = 0; i < 4; ++i) { F[(g + 1) & 1][i] = pf[(g + 1) * 4 + i]; Q[(g + 1) & 1][i] = pf[16 + (g + 1) * 4 + i]; } }
;             __builtin_amdgcn_sched_barrier(0);
; #pragma unroll
;             for (int i = 0; i < 4; ++i) {
;                 const f32x4 f4 = F[g & 1][i], q4 = Q[g & 1][i]; const int idx = (g * 4 + i) * 2;
;                 const f2 f01 = {f4[0], f4[1]}, f23 = {f4[2], f4[3]}, q01 = {q4[0], q4[1]}, q23 = {q4[2], q4[3]};
;                 S[idx] = pfma(f01, S[idx] - v2, v2); o2 = pfma(S[idx], q01, o2);
;                 S[idx + 1] = pfma(f23, S[idx + 1] - v2, v2); o3 = pfma(S[idx + 1], q23, o3);
;             }
;         }
;         OHp[(size_t)(t0 + s) * 512 + h * 128 + half * 64 + lane] = f2bf((o2[0] + o2[1]) + (o3[0] + o3[1]));
	v_pk_fma_f32 v[32:33], v[148:149], v[32:33], v[250:251] op_sel_hi:[1,1,0]
	v_pk_fma_f32 v[34:35], v[150:151], v[34:35], v[250:251] op_sel_hi:[1,1,0]
	v_pk_fma_f32 v[36:37], v[152:153], v[36:37], v[250:251] op_sel_hi:[1,1,0]
	v_pk_fma_f32 v[38:39], v[154:155], v[38:39], v[250:251] op_sel_hi:[1,1,0]
	v_pk_fma_f32 v[240:241], v[32:33], v[164:165], v[240:241]
	v_pk_fma_f32 v[244:245], v[34:35], v[166:167], v[244:245]
	v_pk_fma_f32 v[240:241], v[36:37], v[168:169], v[240:241]
	v_pk_fma_f32 v[244:245], v[38:39], v[170:171], v[244:245]
	v_pk_fma_f32 v[40:41], v[156:157], v[40:41], v[250:251] op_sel_hi:[1,1,0]
	v_pk_fma_f32 v[42:43], v[158:159], v[42:43], v[250:251] op_sel_hi:[1,1,0]
	v_pk_fma_f32 v[44:45], v[160:161], v[44:45], v[250:251] op_sel_hi:[1,1,0]
	v_pk_fma_f32 v[46:47], v[162:163], v[46:47], v[250:251] op_sel_hi:[1,1,0]
	v_pk_fma_f32 v[240:241], v[40:41], v[172:173], v[240:241]
	v_pk_fma_f32 v[244:245], v[42:43], v[174:175], v[244:245]
	v_pk_fma_f32 v[240:241], v[44:45], v[176:177], v[240:241]
	v_pk_fma_f32 v[244:245], v[46:47], v[178:179], v[244:245]
	v_pk_fma_f32 v[96:97], v[148:149], v[96:97], v[250:251] op_sel:[0,0,1] op_sel_hi:[1,1,1]
	v_pk_fma_f32 v[98:99], v[150:151], v[98:99], v[250:251] op_sel:[0,0,1] op_sel_hi:[1,1,1]
	v_pk_fma_f32 v[100:101], v[152:153], v[100:101], v[250:251] op_sel:[0,0,1] op_sel_hi:[1,1,1]
	v_pk_fma_f32 v[102:103], v[154:155], v[102:103], v[250:251] op_sel:[0,0,1] op_sel_hi:[1,1,1]
	v_pk_fma_f32 v[246:247], v[96:97], v[164:165], v[246:247]
	v_pk_fma_f32 v[248:249], v[98:99], v[166:167], v[248:249]
	v_pk_fma_f32 v[246:247], v[100:101], v[168:169], v[246:247]
	v_pk_fma_f32 v[248:249], v[102:103], v[170:171], v[248:249]
	v_pk_fma_f32 v[104:105], v[156:157], v[104:105], v[250:251] op_sel:[0,0,1] op_sel_hi:[1,1,1]
	v_pk_fma_f32 v[106:107], v[158:159], v[106:107], v[250:251] op_sel:[0,0,1] op_sel_hi:[1,1,1]
	v_pk_fma_f32 v[108:109], v[160:161], v[108:109], v[250:251] op_sel:[0,0,1] op_sel_hi:[1,1,1]
	v_pk_fma_f32 v[110:111], v[162:163], v[110:111], v[250:251] op_sel:[0,0,1] op_sel_hi:[1,1,1]
	v_pk_fma_f32 v[246:247], v[104:105], v[172:173], v[246:247]
	v_pk_fma_f32 v[248:249], v[106:107], v[174:175], v[248:249]
	v_pk_fma_f32 v[246:247], v[108:109], v[176:177], v[246:247]
	v_pk_fma_f32 v[248:249], v[110:111], v[178:179], v[248:249]
	v_add_f32_dpp v182, v182, v182 row_mirror row_mask:0xf bank_mask:0xf bound_ctrl:1
	ds_read_b128 v[148:151], v135 offset:0
	ds_read_b128 v[152:155], v135 offset:16
	ds_read_b128 v[156:159], v135 offset:32
	ds_read_b128 v[160:163], v135 offset:48
	ds_read_b128 v[164:167], v135 offset:256
	ds_read_b128 v[168:171], v135 offset:272
	ds_read_b128 v[172:175], v135 offset:288
	ds_read_b128 v[176:179], v135 offset:304
	v_readlane_b32 s0, v182, 0
	v_readlane_b32 s1, v182, 16
	v_readlane_b32 s6, v182, 32
	v_readlane_b32 s7, v182, 48
	s_waitcnt lgkmcnt(8)
	v_pk_fma_f32 v[48:49], v[192:193], v[48:49], v[250:251] op_sel_hi:[1,1,0]
	v_pk_fma_f32 v[50:51], v[194:195], v[50:51], v[250:251] op_sel_hi:[1,1,0]
	v_pk_fma_f32 v[52:53], v[196:197], v[52:53], v[250:251] op_sel_hi:[1,1,0]
	v_pk_fma_f32 v[54:55], v[198:199], v[54:55], v[250:251] op_sel_hi:[1,1,0]
	v_pk_fma_f32 v[240:241], v[48:49], v[208:209], v[240:241]
	v_pk_fma_f32 v[244:245], v[50:51], v[210:211], v[244:245]
	v_pk_fma_f32 v[240:241], v[52:53], v[212:213], v[240:241]
	v_pk_fma_f32 v[244:245], v[54:55], v[214:215], v[244:245]
	v_pk_fma_f32 v[56:57], v[200:201], v[56:57], v[250:251] op_sel_hi:[1,1,0]
	v_pk_fma_f32 v[58:59], v[202:203], v[58:59], v[250:251] op_sel_hi:[1,1,0]
	v_pk_fma_f32 v[60:61], v[204:205], v[60:61], v[250:251] op_sel_hi:[1,1,0]
	v_pk_fma_f32 v[62:63], v[206:207], v[62:63], v[250:251] op_sel_hi:[1,1,0]
	v_pk_fma_f32 v[240:241], v[56:57], v[216:217], v[240:241]
	v_pk_fma_f32 v[244:245], v[58:59], v[218:219], v[244:245]
	v_pk_fma_f32 v[240:241], v[60:61], v[220:221], v[240:241]
	v_pk_fma_f32 v[244:245], v[62:63], v[222:223], v[244:245]
	v_pk_fma_f32 v[112:113], v[192:193], v[112:113], v[250:251] op_sel:[0,0,1] op_sel_hi:[1,1,1]
	v_pk_fma_f32 v[114:115], v[194:195], v[114:115], v[250:251] op_sel:[0,0,1] op_sel_hi:[1,1,1]
	v_pk_fma_f32 v[116:117], v[196:197], v[116:117], v[250:251] op_sel:[0,0,1] op_sel_hi:[1,1,1]
	v_pk_fma_f32 v[118:119], v[198:199], v[118:119], v[250:251] op_sel:[0,0,1] op_sel_hi:[1,1,1]
	v_pk_fma_f32 v[246:247], v[112:113], v[208:209], v[246:247]
	v_pk_fma_f32 v[248:249], v[114:115], v[210:211], v[248:249]
	v_pk_fma_f32 v[246:247], v[116:117], v[212:213], v[246:247]
	v_pk_fma_f32 v[248:249], v[118:119], v[214:215], v[248:249]
	v_pk_fma_f32 v[120:121], v[200:201], v[120:121], v[250:251] op_sel:[0,0,1] op_sel_hi:[1,1,1]
	v_pk_fma_f32 v[122:123], v[202:203], v[122:123], v[250:251] op_sel:[0,0,1] op_sel_hi:[1,1,1]
	v_pk_fma_f32 v[124:125], v[204:205], v[124:125], v[250:251] op_sel:[0,0,1] op_sel_hi:[1,1,1]
	v_pk_fma_f32 v[126:127], v[206:207], v[126:127], v[250:251] op_sel:[0,0,1] op_sel_hi:[1,1,1]
	v_pk_fma_f32 v[246:247], v[120:121], v[216:217], v[246:247]
	v_pk_fma_f32 v[248:249], v[122:123], v[218:219], v[248:249]
	v_pk_fma_f32 v[246:247], v[124:125], v[220:221], v[246:247]
	v_pk_fma_f32 v[248:249], v[126:127], v[222:223], v[248:249]
	v_mov_b32_e32 v183, s0
	v_add_f32_e32 v183, s1, v183
	v_add_f32_e32 v183, s6, v183
	v_add_f32_e32 v183, s7, v183
	v_add_f32_e32 v240, v240, v241
	v_add_f32_e32 v244, v244, v245
	v_add_f32_e32 v240, v240, v244
	v_fmac_f32_e32 v240, s2, v254
	v_bfe_u32 v244, v240, 16, 1
	v_add3_u32 v240, v240, v244, s69
	global_store_short_d16_hi v138, v240, s[26:27]
	v_add_f32_e32 v246, v246, v247
	v_add_f32_e32 v248, v248, v249
	v_add_f32_e32 v246, v246, v248
	v_fmac_f32_e32 v246, s2, v255
	v_bfe_u32 v248, v246, 16, 1
	v_add3_u32 v246, v246, v248, s69
	global_store_short_d16_hi v138, v246, s[26:27] offset:128
	v_readfirstlane_b32 s2, v183
	v_mov_b64_e32 v[250:251], v[252:253]
	v_mov_b64_e32 v[254:255], v[180:181]
	v_add_u32_e32 v138, 0x400, v138
	s_add_i32 s37, s37, 1
	s_cmp_lg_u32 s37, s36
	s_cbranch_scc1 .Lhs_m_loop
	s_waitcnt vmcnt(0) lgkmcnt(0)
	s_cmp_eq_u32 s38, 4
	s_cbranch_scc1 .Lhs_store
	global_store_dword v147, v133, s[44:45]
